# w_up transposes split over quarter-less WGs of P3 and P4, w_down transposes in P5 tail, cache_k conversion in P1 tail
# speedup vs baseline: 1.0354x; 1.0089x over previous
; #define LAS __attribute__((address_space(3)))
; template <int MODE>
; __device__ __forceinline__ void transpose_item(const float* W, int N, bf16_t* WT, int ldt, int coff, LAS float* scr, int item, int lane, const float* g) {
;     const int nblk = N / 32, kb = item / nblk, nb = item % nblk, k0 = 64 * kb, n0 = 32 * nb;
; #pragma unroll 8
;     for (int i = 0; i < 32; ++i) { const int kk = 2 * i + (lane >> 5); float v = W[(size_t)(k0 + kk) * N + n0 + (lane & 31)]; if (MODE >= 1) v *= g[k0 + kk]; scr[kk * 33 + (lane & 31)] = v; }
; __global__ void __launch_bounds__(512, 2) mk_fwd(Args a) {
;     ...
;         constexpr int I_U = 32 * 352, I_D = 88 * 64;
;         for (int it = gw; it < I_U + I_D; it += NGW) {
;             if (it < I_U) transpose_item<1>(a.in[I_WUP], 2 * DFF, WUP, DM, 0, scr, it, lane, a.in[I_N2]);
.LBB0_642:
	s_cmp_lt_i32 s70, 4
	s_cselect_b64 s[4:5], -1, 0
	s_add_u32 s44, s68, 0x1af00000
	s_addc_u32 s45, s69, 0
	s_add_u32 s6, s68, 0x1db00000
	s_addc_u32 s7, s69, 0
	v_writelane_b32 v250, s6, 20
	s_cmpk_lg_i32 s3, 0x100
	s_movk_i32 s8, 0x200
	v_writelane_b32 v250, s7, 21
	s_cselect_b64 s[6:7], -1, 0
	v_writelane_b32 v250, s6, 26
	s_cmpk_eq_i32 s3, 0x100
	s_nop 0
	v_writelane_b32 v250, s7, 27
	s_cselect_b64 s[6:7], -1, 0
	v_writelane_b32 v250, s6, 24
	s_nop 1
	v_writelane_b32 v250, s7, 25
	s_and_b64 s[6:7], s[6:7], exec
	s_cselect_b32 s88, s8, 0x7fffffff
	s_and_b64 s[4:5], s[4:5], s[0:1]
	s_andn2_b64 vcc, exec, s[4:5]
	s_cbranch_vccnz .LBB0_712
	s_cmpk_lt_i32 s96, 0x400
	s_cbranch_scc1 .LBB0_670
	s_and_b32 s0, s96, 7
	s_lshl_b32 s0, s0, 14
	s_add_i32 s1, s96, 0xfffffc00
	s_cmp_lt_u32 s1, 0x1600
	s_cbranch_scc0 .Ltr_done_p3up
	v_lshrrev_b32_e32 v168, 3, v220
	v_and_b32_e32 v169, 7, v220
	v_mul_u32_u24_e32 v170, 0xb000, v168
	v_lshl_add_u32 v171, v169, 4, v170
	v_add_u32_e32 v172, 0x58000, v171
	v_add_u32_e32 v173, 0xb0000, v171
	v_add_u32_e32 v174, 0x108000, v171
	v_add_u32_e32 v175, 0x160000, v171
	v_add_u32_e32 v177, 0x1b8000, v171
	v_add_u32_e32 v182, 0x210000, v171
	v_add_u32_e32 v183, 0x268000, v171
	v_mul_u32_u24_e32 v170, 0x84, v168
	v_lshl_add_u32 v170, v169, 4, v170
	v_add_u32_e32 v189, s0, v170
	v_mul_u32_u24_e32 v170, 0x420, v169
	v_lshl_add_u32 v170, v168, 2, v170
	v_add_u32_e32 v190, s0, v170
	v_mul_u32_u24_e32 v170, 0x1000, v168
	v_lshl_add_u32 v184, v169, 4, v170
	v_add_u32_e32 v185, 0x8000, v184
	v_add_u32_e32 v186, 0x10000, v184
	v_add_u32_e32 v188, 0x18000, v184
	v_lshlrev_b32_e32 v191, 5, v169
	s_mov_b32 s7, s1
	s_mov_b32 s6, s1
	s_and_b32 s34, s6, 7
	s_lshr_b32 s9, s6, 3
	s_lshr_b32 s40, s9, 5
	s_mul_hi_u32 s40, s40, 0xba2e8ba3
	s_lshr_b32 s40, s40, 3
	s_mul_i32 s41, s40, 0x160
	s_sub_u32 s9, s9, s41
	s_lshl_b32 s40, s40, 3
	s_add_u32 s40, s40, s34
	s_mov_b32 s34, s9
	s_mov_b32 s9, s40
	s_mul_i32 s35, s9, 0x2c0000
	s_lshl_b32 s34, s34, 7
	s_add_u32 s35, s35, s34
	s_add_u32 s10, s22, s35
	s_addc_u32 s11, s23, 0
	global_load_dwordx4 v[0:3], v171, s[10:11]
	global_load_dwordx4 v[4:7], v172, s[10:11]
	global_load_dwordx4 v[8:11], v173, s[10:11]
	global_load_dwordx4 v[12:15], v174, s[10:11]
	global_load_dwordx4 v[16:19], v175, s[10:11]
	global_load_dwordx4 v[20:23], v177, s[10:11]
	global_load_dwordx4 v[24:27], v182, s[10:11]
	global_load_dwordx4 v[28:31], v183, s[10:11]
	s_lshl_b32 s35, s9, 8
	s_add_u32 s32, s20, s35
	s_addc_u32 s33, s21, 0
	global_load_dwordx4 v[144:147], v191, s[32:33]
	global_load_dwordx4 v[148:151], v191, s[32:33] offset:16
	s_add_u32 s6, s6, 0x400
	s_cmp_lt_u32 s6, 0x1600
	s_cbranch_scc0 .Ltr_p1_p3up
	s_and_b32 s34, s6, 7
	s_lshr_b32 s9, s6, 3
	s_lshr_b32 s40, s9, 5
	s_mul_hi_u32 s40, s40, 0xba2e8ba3
	s_lshr_b32 s40, s40, 3
	s_mul_i32 s41, s40, 0x160
	s_sub_u32 s9, s9, s41
	s_lshl_b32 s40, s40, 3
	s_add_u32 s40, s40, s34
	s_mov_b32 s34, s9
	s_mov_b32 s9, s40
	s_mul_i32 s35, s9, 0x2c0000
	s_lshl_b32 s34, s34, 7
	s_add_u32 s35, s35, s34
	s_add_u32 s10, s22, s35
	s_addc_u32 s11, s23, 0
	global_load_dwordx4 v[32:35], v171, s[10:11]
	global_load_dwordx4 v[36:39], v172, s[10:11]
	global_load_dwordx4 v[40:43], v173, s[10:11]
	global_load_dwordx4 v[44:47], v174, s[10:11]
	global_load_dwordx4 v[48:51], v175, s[10:11]
	global_load_dwordx4 v[52:55], v177, s[10:11]
	global_load_dwordx4 v[56:59], v182, s[10:11]
	global_load_dwordx4 v[60:63], v183, s[10:11]
	s_lshl_b32 s35, s9, 8
	s_add_u32 s32, s20, s35
	s_addc_u32 s33, s21, 0
	global_load_dwordx4 v[152:155], v191, s[32:33]
	global_load_dwordx4 v[156:159], v191, s[32:33] offset:16
.Ltr_p1_p3up:
	s_add_u32 s6, s6, 0x400
.Ltr_st0_p3up:
	s_cmp_lt_u32 s6, 0x1600
	s_cbranch_scc0 .Ltr_nl0_p3up
	s_and_b32 s34, s6, 7
	s_lshr_b32 s9, s6, 3
	s_lshr_b32 s40, s9, 5
	s_mul_hi_u32 s40, s40, 0xba2e8ba3
	s_lshr_b32 s40, s40, 3
	s_mul_i32 s41, s40, 0x160
	s_sub_u32 s9, s9, s41
	s_lshl_b32 s40, s40, 3
	s_add_u32 s40, s40, s34
	s_mov_b32 s34, s9
	s_mov_b32 s9, s40
	s_mul_i32 s35, s9, 0x2c0000
	s_lshl_b32 s34, s34, 7
	s_add_u32 s35, s35, s34
	s_add_u32 s10, s22, s35
	s_addc_u32 s11, s23, 0
	global_load_dwordx4 v[64:67], v171, s[10:11]
	global_load_dwordx4 v[68:71], v172, s[10:11]
	global_load_dwordx4 v[72:75], v173, s[10:11]
	global_load_dwordx4 v[76:79], v174, s[10:11]
	global_load_dwordx4 v[80:83], v175, s[10:11]
	global_load_dwordx4 v[84:87], v177, s[10:11]
	global_load_dwordx4 v[88:91], v182, s[10:11]
	global_load_dwordx4 v[92:95], v183, s[10:11]
	s_lshl_b32 s35, s9, 8
	s_add_u32 s32, s20, s35
	s_addc_u32 s33, s21, 0
	global_load_dwordx4 v[160:163], v191, s[32:33]
	global_load_dwordx4 v[164:167], v191, s[32:33] offset:16
	s_waitcnt vmcnt(20)
	s_branch .Ltr_pr0_p3up
.Ltr_nl0_p3up:
	s_sub_u32 s9, s6, 0x400
	s_cmp_lt_u32 s9, 0x1600
	s_cbranch_scc0 .Ltr_w00_p3up
	s_waitcnt vmcnt(10)
	s_branch .Ltr_pr0_p3up

; #define LAS __attribute__((address_space(3)))
; __device__ __forceinline__ unsigned cvtpk(float lo, float hi) { f32x2_t v = {lo, hi}; bf16x2_t b = __builtin_convertvector(v, bf16x2_t); return __builtin_bit_cast(unsigned, b); }
; template <int MODE>
; __device__ __forceinline__ void transpose_item(const float* W, int N, bf16_t* WT, int ldt, int coff, LAS float* scr, int item, int lane, const float* g) {
;     ...
;     for (int i = 0; i < 32; ++i) { const int kk = 2 * i + (lane >> 5); float v = W[(size_t)(k0 + kk) * N + n0 + (lane & 31)]; if (MODE >= 1) v *= g[k0 + kk]; scr[kk * 33 + (lane & 31)] = v; }
;     asm volatile("s_waitcnt lgkmcnt(0)" ::: "memory");
;     const int c = lane & 7;
; #pragma unroll
;     for (int j = 0; j < 4; ++j) {
;         const int n = (lane >> 3) + 8 * j; const LAS float* s = scr + (8 * c) * 33 + n;
;         u32x4 o; o.x = cvtpk(s[0 * 33], s[1 * 33]); o.y = cvtpk(s[2 * 33], s[3 * 33]); o.z = cvtpk(s[4 * 33], s[5 * 33]); o.w = cvtpk(s[6 * 33], s[7 * 33]);
;         int dr = n0 + n;
;         if (MODE == 1) { dr = (dr < DFF) ? 256 * (dr >> 7) + (dr & 127) : 256 * ((dr - DFF) >> 7) + 128 + ((dr - DFF) & 127); }
;         if (MODE == 2) {
;             if (dr >= 6144) { const int t = dr - 6144, ch = t & 2047; dr = 6144 + 256 * (ch >> 7) + ((t >> 11) << 7) + (ch & 127); }
;             else if (dr >= 4096) { const int t = dr - 4096, ch = t & 1023; dr = 4096 + 256 * (ch >> 7) + ((t >> 10) << 7) + (ch & 127); }
;         }
;         *(u32x4*)(WT + (size_t)dr * ldt + coff + k0 + 8 * c) = o;
.Ltr_pr0_p3up:
	s_add_u32 s6, s6, 0x400
	s_and_b32 s34, s7, 7
	s_lshr_b32 s9, s7, 3
	s_lshr_b32 s40, s9, 5
	s_mul_hi_u32 s40, s40, 0xba2e8ba3
	s_lshr_b32 s40, s40, 3
	s_mul_i32 s41, s40, 0x160
	s_sub_u32 s9, s9, s41
	s_lshl_b32 s40, s40, 3
	s_add_u32 s40, s40, s34
	s_mov_b32 s34, s9
	s_mov_b32 s9, s40
	s_cmp_ge_u32 s34, 0xb0
	s_cselect_b32 s35, 0xb0, 0
	s_cselect_b32 s36, 0x80, 0
	s_sub_u32 s34, s34, s35
	s_lshl_b32 s34, s34, 5
	s_and_b32 s35, s34, 0xffffff80
	s_and_b32 s34, s34, 0x7f
	s_lshl_b32 s35, s35, 1
	s_add_u32 s35, s35, s34
	s_add_u32 s35, s35, s36
	s_mul_i32 s35, s35, 0x1000
	s_lshl_b32 s9, s9, 7
	s_add_u32 s35, s35, s9
	s_add_u32 s14, s44, s35
	s_addc_u32 s15, s45, 0
	ds_write_b32 v189, v0 offset:0
	ds_write_b32 v189, v1 offset:4
	ds_write_b32 v189, v2 offset:8
	ds_write_b32 v189, v3 offset:12
	ds_write_b32 v189, v4 offset:1056
	ds_write_b32 v189, v5 offset:1060
	ds_write_b32 v189, v6 offset:1064
	ds_write_b32 v189, v7 offset:1068
	ds_write_b32 v189, v8 offset:2112
	ds_write_b32 v189, v9 offset:2116
	ds_write_b32 v189, v10 offset:2120
	ds_write_b32 v189, v11 offset:2124
	ds_write_b32 v189, v12 offset:3168
	ds_write_b32 v189, v13 offset:3172
	ds_write_b32 v189, v14 offset:3176
	ds_write_b32 v189, v15 offset:3180
	ds_write_b32 v189, v16 offset:4224
	ds_write_b32 v189, v17 offset:4228
	ds_write_b32 v189, v18 offset:4232
	ds_write_b32 v189, v19 offset:4236
	ds_write_b32 v189, v20 offset:5280
	ds_write_b32 v189, v21 offset:5284
	ds_write_b32 v189, v22 offset:5288
	ds_write_b32 v189, v23 offset:5292
	ds_write_b32 v189, v24 offset:6336
	ds_write_b32 v189, v25 offset:6340
	ds_write_b32 v189, v26 offset:6344
	ds_write_b32 v189, v27 offset:6348
	ds_write_b32 v189, v28 offset:7392
	ds_write_b32 v189, v29 offset:7396
	ds_write_b32 v189, v30 offset:7400
	ds_write_b32 v189, v31 offset:7404
	s_waitcnt lgkmcnt(0)
	ds_read2_b32 v[96:97], v190 offset0:0 offset1:8
	ds_read2_b32 v[100:101], v190 offset0:33 offset1:41
	ds_read2_b32 v[104:105], v190 offset0:66 offset1:74
	ds_read2_b32 v[108:109], v190 offset0:99 offset1:107
	ds_read2_b32 v[112:113], v190 offset0:132 offset1:140
	ds_read2_b32 v[116:117], v190 offset0:165 offset1:173
	ds_read2_b32 v[120:121], v190 offset0:198 offset1:206
	ds_read2_b32 v[124:125], v190 offset0:231 offset1:239
	ds_read2_b32 v[98:99], v190 offset0:16 offset1:24
	ds_read2_b32 v[102:103], v190 offset0:49 offset1:57
	ds_read2_b32 v[106:107], v190 offset0:82 offset1:90
	ds_read2_b32 v[110:111], v190 offset0:115 offset1:123
	ds_read2_b32 v[114:115], v190 offset0:148 offset1:156
	ds_read2_b32 v[118:119], v190 offset0:181 offset1:189
	ds_read2_b32 v[122:123], v190 offset0:214 offset1:222
	ds_read2_b32 v[126:127], v190 offset0:247 offset1:255
	s_waitcnt lgkmcnt(0)
	v_mul_f32_e32 v96, v144, v96
	v_mul_f32_e32 v97, v144, v97
	v_mul_f32_e32 v98, v144, v98
	v_mul_f32_e32 v99, v144, v99
	v_mul_f32_e32 v100, v145, v100
	v_mul_f32_e32 v101, v145, v101
	v_mul_f32_e32 v102, v145, v102
	v_mul_f32_e32 v103, v145, v103
	v_mul_f32_e32 v104, v146, v104
	v_mul_f32_e32 v105, v146, v105
	v_mul_f32_e32 v106, v146, v106
	v_mul_f32_e32 v107, v146, v107
	v_mul_f32_e32 v108, v147, v108
	v_mul_f32_e32 v109, v147, v109
	v_mul_f32_e32 v110, v147, v110
	v_mul_f32_e32 v111, v147, v111
	v_mul_f32_e32 v112, v148, v112
	v_mul_f32_e32 v113, v148, v113
	v_mul_f32_e32 v114, v148, v114
	v_mul_f32_e32 v115, v148, v115
	v_mul_f32_e32 v116, v149, v116
	v_mul_f32_e32 v117, v149, v117
	v_mul_f32_e32 v118, v149, v118
	v_mul_f32_e32 v119, v149, v119
	v_mul_f32_e32 v120, v150, v120
	v_mul_f32_e32 v121, v150, v121
	v_mul_f32_e32 v122, v150, v122
	v_mul_f32_e32 v123, v150, v123
	v_mul_f32_e32 v124, v151, v124
	v_mul_f32_e32 v125, v151, v125
	v_mul_f32_e32 v126, v151, v126
	v_mul_f32_e32 v127, v151, v127
	v_cvt_pk_bf16_f32 v128, v96, v100
	v_cvt_pk_bf16_f32 v129, v104, v108
	v_cvt_pk_bf16_f32 v130, v112, v116
	v_cvt_pk_bf16_f32 v131, v120, v124
	global_store_dwordx4 v184, v[128:131], s[14:15]
	v_cvt_pk_bf16_f32 v132, v97, v101
	v_cvt_pk_bf16_f32 v133, v105, v109
	v_cvt_pk_bf16_f32 v134, v113, v117
	v_cvt_pk_bf16_f32 v135, v121, v125
	global_store_dwordx4 v185, v[132:135], s[14:15]
	v_cvt_pk_bf16_f32 v136, v98, v102
	v_cvt_pk_bf16_f32 v137, v106, v110
	v_cvt_pk_bf16_f32 v138, v114, v118
	v_cvt_pk_bf16_f32 v139, v122, v126
	global_store_dwordx4 v186, v[136:139], s[14:15]
	v_cvt_pk_bf16_f32 v140, v99, v103
	v_cvt_pk_bf16_f32 v141, v107, v111
	v_cvt_pk_bf16_f32 v142, v115, v119
	v_cvt_pk_bf16_f32 v143, v123, v127
	global_store_dwordx4 v188, v[140:143], s[14:15]
	s_add_u32 s7, s7, 0x400
	s_cmp_lt_u32 s7, 0x1600
	s_cbranch_scc0 .Ltr_done_p3up
.Ltr_st1_p3up:
	s_cmp_lt_u32 s6, 0x1600
	s_cbranch_scc0 .Ltr_nl1_p3up
	s_and_b32 s34, s6, 7
	s_lshr_b32 s9, s6, 3
	s_lshr_b32 s40, s9, 5
	s_mul_hi_u32 s40, s40, 0xba2e8ba3
	s_lshr_b32 s40, s40, 3
	s_mul_i32 s41, s40, 0x160
	s_sub_u32 s9, s9, s41
	s_lshl_b32 s40, s40, 3
	s_add_u32 s40, s40, s34
	s_mov_b32 s34, s9
	s_mov_b32 s9, s40
	s_mul_i32 s35, s9, 0x2c0000
	s_lshl_b32 s34, s34, 7
	s_add_u32 s35, s35, s34
	s_add_u32 s10, s22, s35
	s_addc_u32 s11, s23, 0
	global_load_dwordx4 v[0:3], v171, s[10:11]
	global_load_dwordx4 v[4:7], v172, s[10:11]
	global_load_dwordx4 v[8:11], v173, s[10:11]
	global_load_dwordx4 v[12:15], v174, s[10:11]
	global_load_dwordx4 v[16:19], v175, s[10:11]
	global_load_dwordx4 v[20:23], v177, s[10:11]
	global_load_dwordx4 v[24:27], v182, s[10:11]
	global_load_dwordx4 v[28:31], v183, s[10:11]
	s_lshl_b32 s35, s9, 8
	s_add_u32 s32, s20, s35
	s_addc_u32 s33, s21, 0
	global_load_dwordx4 v[144:147], v191, s[32:33]
	global_load_dwordx4 v[148:151], v191, s[32:33] offset:16
	s_waitcnt vmcnt(20)
	s_branch .Ltr_pr1_p3up

; #define LAS __attribute__((address_space(3)))
; __device__ __forceinline__ unsigned cvtpk(float lo, float hi) { f32x2_t v = {lo, hi}; bf16x2_t b = __builtin_convertvector(v, bf16x2_t); return __builtin_bit_cast(unsigned, b); }
; template <int MODE>
; __device__ __forceinline__ void transpose_item(const float* W, int N, bf16_t* WT, int ldt, int coff, LAS float* scr, int item, int lane, const float* g) {
;     ...
;     for (int i = 0; i < 32; ++i) { const int kk = 2 * i + (lane >> 5); float v = W[(size_t)(k0 + kk) * N + n0 + (lane & 31)]; if (MODE >= 1) v *= g[k0 + kk]; scr[kk * 33 + (lane & 31)] = v; }
;     asm volatile("s_waitcnt lgkmcnt(0)" ::: "memory");
;     const int c = lane & 7;
; #pragma unroll
;     for (int j = 0; j < 4; ++j) {
;         const int n = (lane >> 3) + 8 * j; const LAS float* s = scr + (8 * c) * 33 + n;
;         u32x4 o; o.x = cvtpk(s[0 * 33], s[1 * 33]); o.y = cvtpk(s[2 * 33], s[3 * 33]); o.z = cvtpk(s[4 * 33], s[5 * 33]); o.w = cvtpk(s[6 * 33], s[7 * 33]);
;         int dr = n0 + n;
;         if (MODE == 1) { dr = (dr < DFF) ? 256 * (dr >> 7) + (dr & 127) : 256 * ((dr - DFF) >> 7) + 128 + ((dr - DFF) & 127); }
;         if (MODE == 2) {
;             if (dr >= 6144) { const int t = dr - 6144, ch = t & 2047; dr = 6144 + 256 * (ch >> 7) + ((t >> 11) << 7) + (ch & 127); }
;             else if (dr >= 4096) { const int t = dr - 4096, ch = t & 1023; dr = 4096 + 256 * (ch >> 7) + ((t >> 10) << 7) + (ch & 127); }
;         }
;         *(u32x4*)(WT + (size_t)dr * ldt + coff + k0 + 8 * c) = o;
.Ltr_pr1_p3up:
	s_add_u32 s6, s6, 0x400
	s_and_b32 s34, s7, 7
	s_lshr_b32 s9, s7, 3
	s_lshr_b32 s40, s9, 5
	s_mul_hi_u32 s40, s40, 0xba2e8ba3
	s_lshr_b32 s40, s40, 3
	s_mul_i32 s41, s40, 0x160
	s_sub_u32 s9, s9, s41
	s_lshl_b32 s40, s40, 3
	s_add_u32 s40, s40, s34
	s_mov_b32 s34, s9
	s_mov_b32 s9, s40
	s_cmp_ge_u32 s34, 0xb0
	s_cselect_b32 s35, 0xb0, 0
	s_cselect_b32 s36, 0x80, 0
	s_sub_u32 s34, s34, s35
	s_lshl_b32 s34, s34, 5
	s_and_b32 s35, s34, 0xffffff80
	s_and_b32 s34, s34, 0x7f
	s_lshl_b32 s35, s35, 1
	s_add_u32 s35, s35, s34
	s_add_u32 s35, s35, s36
	s_mul_i32 s35, s35, 0x1000
	s_lshl_b32 s9, s9, 7
	s_add_u32 s35, s35, s9
	s_add_u32 s14, s44, s35
	s_addc_u32 s15, s45, 0
	ds_write_b32 v189, v32 offset:0
	ds_write_b32 v189, v33 offset:4
	ds_write_b32 v189, v34 offset:8
	ds_write_b32 v189, v35 offset:12
	ds_write_b32 v189, v36 offset:1056
	ds_write_b32 v189, v37 offset:1060
	ds_write_b32 v189, v38 offset:1064
	ds_write_b32 v189, v39 offset:1068
	ds_write_b32 v189, v40 offset:2112
	ds_write_b32 v189, v41 offset:2116
	ds_write_b32 v189, v42 offset:2120
	ds_write_b32 v189, v43 offset:2124
	ds_write_b32 v189, v44 offset:3168
	ds_write_b32 v189, v45 offset:3172
	ds_write_b32 v189, v46 offset:3176
	ds_write_b32 v189, v47 offset:3180
	ds_write_b32 v189, v48 offset:4224
	ds_write_b32 v189, v49 offset:4228
	ds_write_b32 v189, v50 offset:4232
	ds_write_b32 v189, v51 offset:4236
	ds_write_b32 v189, v52 offset:5280
	ds_write_b32 v189, v53 offset:5284
	ds_write_b32 v189, v54 offset:5288
	ds_write_b32 v189, v55 offset:5292
	ds_write_b32 v189, v56 offset:6336
	ds_write_b32 v189, v57 offset:6340
	ds_write_b32 v189, v58 offset:6344
	ds_write_b32 v189, v59 offset:6348
	ds_write_b32 v189, v60 offset:7392
	ds_write_b32 v189, v61 offset:7396
	ds_write_b32 v189, v62 offset:7400
	ds_write_b32 v189, v63 offset:7404
	s_waitcnt lgkmcnt(0)
	ds_read2_b32 v[96:97], v190 offset0:0 offset1:8
	ds_read2_b32 v[100:101], v190 offset0:33 offset1:41
	ds_read2_b32 v[104:105], v190 offset0:66 offset1:74
	ds_read2_b32 v[108:109], v190 offset0:99 offset1:107
	ds_read2_b32 v[112:113], v190 offset0:132 offset1:140
	ds_read2_b32 v[116:117], v190 offset0:165 offset1:173
	ds_read2_b32 v[120:121], v190 offset0:198 offset1:206
	ds_read2_b32 v[124:125], v190 offset0:231 offset1:239
	ds_read2_b32 v[98:99], v190 offset0:16 offset1:24
	ds_read2_b32 v[102:103], v190 offset0:49 offset1:57
	ds_read2_b32 v[106:107], v190 offset0:82 offset1:90
	ds_read2_b32 v[110:111], v190 offset0:115 offset1:123
	ds_read2_b32 v[114:115], v190 offset0:148 offset1:156
	ds_read2_b32 v[118:119], v190 offset0:181 offset1:189
	ds_read2_b32 v[122:123], v190 offset0:214 offset1:222
	ds_read2_b32 v[126:127], v190 offset0:247 offset1:255
	s_waitcnt lgkmcnt(0)
	v_mul_f32_e32 v96, v152, v96
	v_mul_f32_e32 v97, v152, v97
	v_mul_f32_e32 v98, v152, v98
	v_mul_f32_e32 v99, v152, v99
	v_mul_f32_e32 v100, v153, v100
	v_mul_f32_e32 v101, v153, v101
	v_mul_f32_e32 v102, v153, v102
	v_mul_f32_e32 v103, v153, v103
	v_mul_f32_e32 v104, v154, v104
	v_mul_f32_e32 v105, v154, v105
	v_mul_f32_e32 v106, v154, v106
	v_mul_f32_e32 v107, v154, v107
	v_mul_f32_e32 v108, v155, v108
	v_mul_f32_e32 v109, v155, v109
	v_mul_f32_e32 v110, v155, v110
	v_mul_f32_e32 v111, v155, v111
	v_mul_f32_e32 v112, v156, v112
	v_mul_f32_e32 v113, v156, v113
	v_mul_f32_e32 v114, v156, v114
	v_mul_f32_e32 v115, v156, v115
	v_mul_f32_e32 v116, v157, v116
	v_mul_f32_e32 v117, v157, v117
	v_mul_f32_e32 v118, v157, v118
	v_mul_f32_e32 v119, v157, v119
	v_mul_f32_e32 v120, v158, v120
	v_mul_f32_e32 v121, v158, v121
	v_mul_f32_e32 v122, v158, v122
	v_mul_f32_e32 v123, v158, v123
	v_mul_f32_e32 v124, v159, v124
	v_mul_f32_e32 v125, v159, v125
	v_mul_f32_e32 v126, v159, v126
	v_mul_f32_e32 v127, v159, v127
	v_cvt_pk_bf16_f32 v128, v96, v100
	v_cvt_pk_bf16_f32 v129, v104, v108
	v_cvt_pk_bf16_f32 v130, v112, v116
	v_cvt_pk_bf16_f32 v131, v120, v124
	global_store_dwordx4 v184, v[128:131], s[14:15]
	v_cvt_pk_bf16_f32 v132, v97, v101
	v_cvt_pk_bf16_f32 v133, v105, v109
	v_cvt_pk_bf16_f32 v134, v113, v117
	v_cvt_pk_bf16_f32 v135, v121, v125
	global_store_dwordx4 v185, v[132:135], s[14:15]
	v_cvt_pk_bf16_f32 v136, v98, v102
	v_cvt_pk_bf16_f32 v137, v106, v110
	v_cvt_pk_bf16_f32 v138, v114, v118
	v_cvt_pk_bf16_f32 v139, v122, v126
	global_store_dwordx4 v186, v[136:139], s[14:15]
	v_cvt_pk_bf16_f32 v140, v99, v103
	v_cvt_pk_bf16_f32 v141, v107, v111
	v_cvt_pk_bf16_f32 v142, v115, v119
	v_cvt_pk_bf16_f32 v143, v123, v127
	global_store_dwordx4 v188, v[140:143], s[14:15]
	s_add_u32 s7, s7, 0x400
	s_cmp_lt_u32 s7, 0x1600
	s_cbranch_scc0 .Ltr_done_p3up
.Ltr_st2_p3up:
	s_cmp_lt_u32 s6, 0x1600
	s_cbranch_scc0 .Ltr_nl2_p3up
	s_and_b32 s34, s6, 7
	s_lshr_b32 s9, s6, 3
	s_lshr_b32 s40, s9, 5
	s_mul_hi_u32 s40, s40, 0xba2e8ba3
	s_lshr_b32 s40, s40, 3
	s_mul_i32 s41, s40, 0x160
	s_sub_u32 s9, s9, s41
	s_lshl_b32 s40, s40, 3
	s_add_u32 s40, s40, s34
	s_mov_b32 s34, s9
	s_mov_b32 s9, s40
	s_mul_i32 s35, s9, 0x2c0000
	s_lshl_b32 s34, s34, 7
	s_add_u32 s35, s35, s34
	s_add_u32 s10, s22, s35
	s_addc_u32 s11, s23, 0
	global_load_dwordx4 v[32:35], v171, s[10:11]
	global_load_dwordx4 v[36:39], v172, s[10:11]
	global_load_dwordx4 v[40:43], v173, s[10:11]
	global_load_dwordx4 v[44:47], v174, s[10:11]
	global_load_dwordx4 v[48:51], v175, s[10:11]
	global_load_dwordx4 v[52:55], v177, s[10:11]
	global_load_dwordx4 v[56:59], v182, s[10:11]
	global_load_dwordx4 v[60:63], v183, s[10:11]
	s_lshl_b32 s35, s9, 8
	s_add_u32 s32, s20, s35
	s_addc_u32 s33, s21, 0
	global_load_dwordx4 v[152:155], v191, s[32:33]
	global_load_dwordx4 v[156:159], v191, s[32:33] offset:16
	s_waitcnt vmcnt(20)
	s_branch .Ltr_pr2_p3up

; #define LAS __attribute__((address_space(3)))
; __device__ __forceinline__ unsigned cvtpk(float lo, float hi) { f32x2_t v = {lo, hi}; bf16x2_t b = __builtin_convertvector(v, bf16x2_t); return __builtin_bit_cast(unsigned, b); }
; template <int MODE>
; __device__ __forceinline__ void transpose_item(const float* W, int N, bf16_t* WT, int ldt, int coff, LAS float* scr, int item, int lane, const float* g) {
;     ...
;     for (int i = 0; i < 32; ++i) { const int kk = 2 * i + (lane >> 5); float v = W[(size_t)(k0 + kk) * N + n0 + (lane & 31)]; if (MODE >= 1) v *= g[k0 + kk]; scr[kk * 33 + (lane & 31)] = v; }
;     asm volatile("s_waitcnt lgkmcnt(0)" ::: "memory");
;     const int c = lane & 7;
; #pragma unroll
;     for (int j = 0; j < 4; ++j) {
;         const int n = (lane >> 3) + 8 * j; const LAS float* s = scr + (8 * c) * 33 + n;
;         u32x4 o; o.x = cvtpk(s[0 * 33], s[1 * 33]); o.y = cvtpk(s[2 * 33], s[3 * 33]); o.z = cvtpk(s[4 * 33], s[5 * 33]); o.w = cvtpk(s[6 * 33], s[7 * 33]);
;         int dr = n0 + n;
;         if (MODE == 1) { dr = (dr < DFF) ? 256 * (dr >> 7) + (dr & 127) : 256 * ((dr - DFF) >> 7) + 128 + ((dr - DFF) & 127); }
;         if (MODE == 2) {
;             if (dr >= 6144) { const int t = dr - 6144, ch = t & 2047; dr = 6144 + 256 * (ch >> 7) + ((t >> 11) << 7) + (ch & 127); }
;             else if (dr >= 4096) { const int t = dr - 4096, ch = t & 1023; dr = 4096 + 256 * (ch >> 7) + ((t >> 10) << 7) + (ch & 127); }
;         }
;         *(u32x4*)(WT + (size_t)dr * ldt + coff + k0 + 8 * c) = o;
.Ltr_pr2_p3up:
	s_add_u32 s6, s6, 0x400
	s_and_b32 s34, s7, 7
	s_lshr_b32 s9, s7, 3
	s_lshr_b32 s40, s9, 5
	s_mul_hi_u32 s40, s40, 0xba2e8ba3
	s_lshr_b32 s40, s40, 3
	s_mul_i32 s41, s40, 0x160
	s_sub_u32 s9, s9, s41
	s_lshl_b32 s40, s40, 3
	s_add_u32 s40, s40, s34
	s_mov_b32 s34, s9
	s_mov_b32 s9, s40
	s_cmp_ge_u32 s34, 0xb0
	s_cselect_b32 s35, 0xb0, 0
	s_cselect_b32 s36, 0x80, 0
	s_sub_u32 s34, s34, s35
	s_lshl_b32 s34, s34, 5
	s_and_b32 s35, s34, 0xffffff80
	s_and_b32 s34, s34, 0x7f
	s_lshl_b32 s35, s35, 1
	s_add_u32 s35, s35, s34
	s_add_u32 s35, s35, s36
	s_mul_i32 s35, s35, 0x1000
	s_lshl_b32 s9, s9, 7
	s_add_u32 s35, s35, s9
	s_add_u32 s14, s44, s35
	s_addc_u32 s15, s45, 0
	ds_write_b32 v189, v64 offset:0
	ds_write_b32 v189, v65 offset:4
	ds_write_b32 v189, v66 offset:8
	ds_write_b32 v189, v67 offset:12
	ds_write_b32 v189, v68 offset:1056
	ds_write_b32 v189, v69 offset:1060
	ds_write_b32 v189, v70 offset:1064
	ds_write_b32 v189, v71 offset:1068
	ds_write_b32 v189, v72 offset:2112
	ds_write_b32 v189, v73 offset:2116
	ds_write_b32 v189, v74 offset:2120
	ds_write_b32 v189, v75 offset:2124
	ds_write_b32 v189, v76 offset:3168
	ds_write_b32 v189, v77 offset:3172
	ds_write_b32 v189, v78 offset:3176
	ds_write_b32 v189, v79 offset:3180
	ds_write_b32 v189, v80 offset:4224
	ds_write_b32 v189, v81 offset:4228
	ds_write_b32 v189, v82 offset:4232
	ds_write_b32 v189, v83 offset:4236
	ds_write_b32 v189, v84 offset:5280
	ds_write_b32 v189, v85 offset:5284
	ds_write_b32 v189, v86 offset:5288
	ds_write_b32 v189, v87 offset:5292
	ds_write_b32 v189, v88 offset:6336
	ds_write_b32 v189, v89 offset:6340
	ds_write_b32 v189, v90 offset:6344
	ds_write_b32 v189, v91 offset:6348
	ds_write_b32 v189, v92 offset:7392
	ds_write_b32 v189, v93 offset:7396
	ds_write_b32 v189, v94 offset:7400
	ds_write_b32 v189, v95 offset:7404
	s_waitcnt lgkmcnt(0)
	ds_read2_b32 v[96:97], v190 offset0:0 offset1:8
	ds_read2_b32 v[100:101], v190 offset0:33 offset1:41
	ds_read2_b32 v[104:105], v190 offset0:66 offset1:74
	ds_read2_b32 v[108:109], v190 offset0:99 offset1:107
	ds_read2_b32 v[112:113], v190 offset0:132 offset1:140
	ds_read2_b32 v[116:117], v190 offset0:165 offset1:173
	ds_read2_b32 v[120:121], v190 offset0:198 offset1:206
	ds_read2_b32 v[124:125], v190 offset0:231 offset1:239
	ds_read2_b32 v[98:99], v190 offset0:16 offset1:24
	ds_read2_b32 v[102:103], v190 offset0:49 offset1:57
	ds_read2_b32 v[106:107], v190 offset0:82 offset1:90
	ds_read2_b32 v[110:111], v190 offset0:115 offset1:123
	ds_read2_b32 v[114:115], v190 offset0:148 offset1:156
	ds_read2_b32 v[118:119], v190 offset0:181 offset1:189
	ds_read2_b32 v[122:123], v190 offset0:214 offset1:222
	ds_read2_b32 v[126:127], v190 offset0:247 offset1:255
	s_waitcnt lgkmcnt(0)
	v_mul_f32_e32 v96, v160, v96
	v_mul_f32_e32 v97, v160, v97
	v_mul_f32_e32 v98, v160, v98
	v_mul_f32_e32 v99, v160, v99
	v_mul_f32_e32 v100, v161, v100
	v_mul_f32_e32 v101, v161, v101
	v_mul_f32_e32 v102, v161, v102
	v_mul_f32_e32 v103, v161, v103
	v_mul_f32_e32 v104, v162, v104
	v_mul_f32_e32 v105, v162, v105
	v_mul_f32_e32 v106, v162, v106
	v_mul_f32_e32 v107, v162, v107
	v_mul_f32_e32 v108, v163, v108
	v_mul_f32_e32 v109, v163, v109
	v_mul_f32_e32 v110, v163, v110
	v_mul_f32_e32 v111, v163, v111
	v_mul_f32_e32 v112, v164, v112
	v_mul_f32_e32 v113, v164, v113
	v_mul_f32_e32 v114, v164, v114
	v_mul_f32_e32 v115, v164, v115
	v_mul_f32_e32 v116, v165, v116
	v_mul_f32_e32 v117, v165, v117
	v_mul_f32_e32 v118, v165, v118
	v_mul_f32_e32 v119, v165, v119
	v_mul_f32_e32 v120, v166, v120
	v_mul_f32_e32 v121, v166, v121
	v_mul_f32_e32 v122, v166, v122
	v_mul_f32_e32 v123, v166, v123
	v_mul_f32_e32 v124, v167, v124
	v_mul_f32_e32 v125, v167, v125
	v_mul_f32_e32 v126, v167, v126
	v_mul_f32_e32 v127, v167, v127
	v_cvt_pk_bf16_f32 v128, v96, v100
	v_cvt_pk_bf16_f32 v129, v104, v108
	v_cvt_pk_bf16_f32 v130, v112, v116
	v_cvt_pk_bf16_f32 v131, v120, v124
	global_store_dwordx4 v184, v[128:131], s[14:15]
	v_cvt_pk_bf16_f32 v132, v97, v101
	v_cvt_pk_bf16_f32 v133, v105, v109
	v_cvt_pk_bf16_f32 v134, v113, v117
	v_cvt_pk_bf16_f32 v135, v121, v125
	global_store_dwordx4 v185, v[132:135], s[14:15]
	v_cvt_pk_bf16_f32 v136, v98, v102
	v_cvt_pk_bf16_f32 v137, v106, v110
	v_cvt_pk_bf16_f32 v138, v114, v118
	v_cvt_pk_bf16_f32 v139, v122, v126
	global_store_dwordx4 v186, v[136:139], s[14:15]
	v_cvt_pk_bf16_f32 v140, v99, v103
	v_cvt_pk_bf16_f32 v141, v107, v111
	v_cvt_pk_bf16_f32 v142, v115, v119
	v_cvt_pk_bf16_f32 v143, v123, v127
	global_store_dwordx4 v188, v[140:143], s[14:15]
	s_add_u32 s7, s7, 0x400
	s_cmp_lt_u32 s7, 0x1600
	s_cbranch_scc0 .Ltr_done_p3up
	s_branch .Ltr_st0_p3up

; #define LAS __attribute__((address_space(3)))
; __device__ __forceinline__ unsigned cvtpk(float lo, float hi) { f32x2_t v = {lo, hi}; bf16x2_t b = __builtin_convertvector(v, bf16x2_t); return __builtin_bit_cast(unsigned, b); }
; template <int MODE>
; __device__ __forceinline__ void transpose_item(const float* W, int N, bf16_t* WT, int ldt, int coff, LAS float* scr, int item, int lane, const float* g) {
;     const int nblk = N / 32, kb = item / nblk, nb = item % nblk, k0 = 64 * kb, n0 = 32 * nb;
; #pragma unroll 8
;     for (int i = 0; i < 32; ++i) { const int kk = 2 * i + (lane >> 5); float v = W[(size_t)(k0 + kk) * N + n0 + (lane & 31)]; if (MODE >= 1) v *= g[k0 + kk]; scr[kk * 33 + (lane & 31)] = v; }
;     asm volatile("s_waitcnt lgkmcnt(0)" ::: "memory");
;     const int c = lane & 7;
; #pragma unroll
;     for (int j = 0; j < 4; ++j) {
;         const int n = (lane >> 3) + 8 * j; const LAS float* s = scr + (8 * c) * 33 + n;
;         u32x4 o; o.x = cvtpk(s[0 * 33], s[1 * 33]); o.y = cvtpk(s[2 * 33], s[3 * 33]); o.z = cvtpk(s[4 * 33], s[5 * 33]); o.w = cvtpk(s[6 * 33], s[7 * 33]);
; __global__ void __launch_bounds__(512, 2) mk_fwd(Args a) {
;     ...
;         for (int it = gw; it < I_U + I_D; it += NGW) {
;             if (it < I_U) transpose_item<1>(a.in[I_WUP], 2 * DFF, WUP, DM, 0, scr, it, lane, a.in[I_N2]);
;             else transpose_item<0>(a.in[I_WDN], DM, WDN, DFF, 0, scr, it - I_U, lane, nullptr);
.LBB0_767:
	s_cmp_lt_i32 s70, 5
	s_cselect_b64 s[4:5], -1, 0
	s_add_u32 s22, s68, 0x10000
	s_addc_u32 s23, s69, 0
	s_and_b64 s[4:5], s[4:5], s[0:1]
	s_andn2_b64 vcc, exec, s[4:5]
	s_cbranch_vccnz .LBB0_830
	s_cmp_eq_u32 s3, 0x100
	s_cbranch_scc0 .Lp4t_done
	s_cmp_ge_u32 s2, 0x80
	s_cbranch_scc0 .Lp4t_done
	v_readlane_b32 s0, v250, 0
	v_readlane_b32 s1, v250, 1
	s_nop 3
	s_sub_u32 s0, s0, 0xd0
	s_subb_u32 s1, s1, 0
	s_load_dwordx2 s[6:7], s[0:1], 0x90
	s_load_dwordx2 s[8:9], s[0:1], 0x98
	s_add_u32 s10, s68, 0x1af00000
	s_addc_u32 s11, s69, 0
	s_lshl_b32 s14, s2, 3
	v_readfirstlane_b32 s15, v179
	s_nop 3
	s_lshr_b32 s15, s15, 6
	s_add_u32 s14, s14, s15
	s_sub_u32 s14, s14, 0x400
	s_lshl_b32 s15, s15, 14
	s_add_u32 s14, s14, 0x1600
	s_waitcnt lgkmcnt(0)
	s_cmp_lt_u32 s14, 0x2c00
	s_cbranch_scc0 .Ltr_done_p4up
	v_lshrrev_b32_e32 v168, 3, v220
	v_and_b32_e32 v169, 7, v220
	v_mul_u32_u24_e32 v170, 0xb000, v168
	v_lshl_add_u32 v171, v169, 4, v170
	v_add_u32_e32 v172, 0x58000, v171
	v_add_u32_e32 v173, 0xb0000, v171
	v_add_u32_e32 v174, 0x108000, v171
	v_add_u32_e32 v175, 0x160000, v171
	v_add_u32_e32 v177, 0x1b8000, v171
	v_add_u32_e32 v180, 0x210000, v171
	v_add_u32_e32 v181, 0x268000, v171
	v_mul_u32_u24_e32 v170, 0x84, v168
	v_lshl_add_u32 v170, v169, 4, v170
	v_add_u32_e32 v186, s15, v170
	v_mul_u32_u24_e32 v170, 0x420, v169
	v_lshl_add_u32 v170, v168, 2, v170
	v_add_u32_e32 v187, s15, v170
	v_mul_u32_u24_e32 v170, 0x1000, v168
	v_lshl_add_u32 v182, v169, 4, v170
	v_add_u32_e32 v183, 0x8000, v182
	v_add_u32_e32 v184, 0x10000, v182
	v_add_u32_e32 v185, 0x18000, v182
	v_lshlrev_b32_e32 v188, 5, v169
	s_mov_b32 s21, s14
	s_mov_b32 s20, s14
	s_and_b32 s37, s20, 7
	s_lshr_b32 s36, s20, 3
	s_lshr_b32 s42, s36, 5
	s_mul_hi_u32 s42, s42, 0xba2e8ba3
	s_lshr_b32 s42, s42, 3
	s_mul_i32 s43, s42, 0x160
	s_sub_u32 s36, s36, s43
	s_lshl_b32 s42, s42, 3
	s_add_u32 s42, s42, s37
	s_mov_b32 s37, s36
	s_mov_b32 s36, s42
	s_mul_i32 s40, s36, 0x2c0000
	s_lshl_b32 s37, s37, 7
	s_add_u32 s40, s40, s37
	s_add_u32 s26, s8, s40
	s_addc_u32 s27, s9, 0
	global_load_dwordx4 v[0:3], v171, s[26:27]
	global_load_dwordx4 v[4:7], v172, s[26:27]
	global_load_dwordx4 v[8:11], v173, s[26:27]
	global_load_dwordx4 v[12:15], v174, s[26:27]
	global_load_dwordx4 v[16:19], v175, s[26:27]
	global_load_dwordx4 v[20:23], v177, s[26:27]
	global_load_dwordx4 v[24:27], v180, s[26:27]
	global_load_dwordx4 v[28:31], v181, s[26:27]
	s_lshl_b32 s40, s36, 8
	s_add_u32 s34, s6, s40
	s_addc_u32 s35, s7, 0
	global_load_dwordx4 v[144:147], v188, s[34:35]
	global_load_dwordx4 v[148:151], v188, s[34:35] offset:16
	s_add_u32 s20, s20, 0x400
	s_cmp_lt_u32 s20, 0x2c00
	s_cbranch_scc0 .Ltr_p1_p4up
	s_and_b32 s37, s20, 7
	s_lshr_b32 s36, s20, 3
	s_lshr_b32 s42, s36, 5
	s_mul_hi_u32 s42, s42, 0xba2e8ba3
	s_lshr_b32 s42, s42, 3
	s_mul_i32 s43, s42, 0x160
	s_sub_u32 s36, s36, s43
	s_lshl_b32 s42, s42, 3
	s_add_u32 s42, s42, s37
	s_mov_b32 s37, s36
	s_mov_b32 s36, s42
	s_mul_i32 s40, s36, 0x2c0000
	s_lshl_b32 s37, s37, 7
	s_add_u32 s40, s40, s37
	s_add_u32 s26, s8, s40
	s_addc_u32 s27, s9, 0
	global_load_dwordx4 v[32:35], v171, s[26:27]
	global_load_dwordx4 v[36:39], v172, s[26:27]
	global_load_dwordx4 v[40:43], v173, s[26:27]
	global_load_dwordx4 v[44:47], v174, s[26:27]
	global_load_dwordx4 v[48:51], v175, s[26:27]
	global_load_dwordx4 v[52:55], v177, s[26:27]
	global_load_dwordx4 v[56:59], v180, s[26:27]
	global_load_dwordx4 v[60:63], v181, s[26:27]
	s_lshl_b32 s40, s36, 8
	s_add_u32 s34, s6, s40
	s_addc_u32 s35, s7, 0
	global_load_dwordx4 v[152:155], v188, s[34:35]
	global_load_dwordx4 v[156:159], v188, s[34:35] offset:16
.Ltr_p1_p4up:
	s_add_u32 s20, s20, 0x400
.Ltr_st0_p4up:
	s_cmp_lt_u32 s20, 0x2c00
	s_cbranch_scc0 .Ltr_nl0_p4up
	s_and_b32 s37, s20, 7
	s_lshr_b32 s36, s20, 3
	s_lshr_b32 s42, s36, 5
	s_mul_hi_u32 s42, s42, 0xba2e8ba3
	s_lshr_b32 s42, s42, 3
	s_mul_i32 s43, s42, 0x160
	s_sub_u32 s36, s36, s43
	s_lshl_b32 s42, s42, 3
	s_add_u32 s42, s42, s37
	s_mov_b32 s37, s36
	s_mov_b32 s36, s42
	s_mul_i32 s40, s36, 0x2c0000
	s_lshl_b32 s37, s37, 7
	s_add_u32 s40, s40, s37
	s_add_u32 s26, s8, s40
	s_addc_u32 s27, s9, 0
	global_load_dwordx4 v[64:67], v171, s[26:27]
	global_load_dwordx4 v[68:71], v172, s[26:27]
	global_load_dwordx4 v[72:75], v173, s[26:27]
	global_load_dwordx4 v[76:79], v174, s[26:27]
	global_load_dwordx4 v[80:83], v175, s[26:27]
	global_load_dwordx4 v[84:87], v177, s[26:27]
	global_load_dwordx4 v[88:91], v180, s[26:27]
	global_load_dwordx4 v[92:95], v181, s[26:27]
	s_lshl_b32 s40, s36, 8
	s_add_u32 s34, s6, s40
	s_addc_u32 s35, s7, 0
	global_load_dwordx4 v[160:163], v188, s[34:35]
	global_load_dwordx4 v[164:167], v188, s[34:35] offset:16
	s_waitcnt vmcnt(20)
	s_branch .Ltr_pr0_p4up
.Ltr_nl0_p4up:
	s_sub_u32 s36, s20, 0x400
	s_cmp_lt_u32 s36, 0x2c00
	s_cbranch_scc0 .Ltr_w00_p4up
	s_waitcnt vmcnt(10)
	s_branch .Ltr_pr0_p4up

; #define LAS __attribute__((address_space(3)))
; __device__ __forceinline__ unsigned cvtpk(float lo, float hi) { f32x2_t v = {lo, hi}; bf16x2_t b = __builtin_convertvector(v, bf16x2_t); return __builtin_bit_cast(unsigned, b); }
; template <int MODE>
; __device__ __forceinline__ void transpose_item(const float* W, int N, bf16_t* WT, int ldt, int coff, LAS float* scr, int item, int lane, const float* g) {
;     ...
;     for (int i = 0; i < 32; ++i) { const int kk = 2 * i + (lane >> 5); float v = W[(size_t)(k0 + kk) * N + n0 + (lane & 31)]; if (MODE >= 1) v *= g[k0 + kk]; scr[kk * 33 + (lane & 31)] = v; }
;     asm volatile("s_waitcnt lgkmcnt(0)" ::: "memory");
;     const int c = lane & 7;
; #pragma unroll
;     for (int j = 0; j < 4; ++j) {
;         const int n = (lane >> 3) + 8 * j; const LAS float* s = scr + (8 * c) * 33 + n;
;         u32x4 o; o.x = cvtpk(s[0 * 33], s[1 * 33]); o.y = cvtpk(s[2 * 33], s[3 * 33]); o.z = cvtpk(s[4 * 33], s[5 * 33]); o.w = cvtpk(s[6 * 33], s[7 * 33]);
;         int dr = n0 + n;
;         if (MODE == 1) { dr = (dr < DFF) ? 256 * (dr >> 7) + (dr & 127) : 256 * ((dr - DFF) >> 7) + 128 + ((dr - DFF) & 127); }
;         if (MODE == 2) {
;             if (dr >= 6144) { const int t = dr - 6144, ch = t & 2047; dr = 6144 + 256 * (ch >> 7) + ((t >> 11) << 7) + (ch & 127); }
;             else if (dr >= 4096) { const int t = dr - 4096, ch = t & 1023; dr = 4096 + 256 * (ch >> 7) + ((t >> 10) << 7) + (ch & 127); }
;         }
;         *(u32x4*)(WT + (size_t)dr * ldt + coff + k0 + 8 * c) = o;
;     }
.Ltr_pr0_p4up:
	s_add_u32 s20, s20, 0x400
	s_and_b32 s37, s21, 7
	s_lshr_b32 s36, s21, 3
	s_lshr_b32 s42, s36, 5
	s_mul_hi_u32 s42, s42, 0xba2e8ba3
	s_lshr_b32 s42, s42, 3
	s_mul_i32 s43, s42, 0x160
	s_sub_u32 s36, s36, s43
	s_lshl_b32 s42, s42, 3
	s_add_u32 s42, s42, s37
	s_mov_b32 s37, s36
	s_mov_b32 s36, s42
	s_cmp_ge_u32 s37, 0xb0
	s_cselect_b32 s40, 0xb0, 0
	s_cselect_b32 s41, 0x80, 0
	s_sub_u32 s37, s37, s40
	s_lshl_b32 s37, s37, 5
	s_and_b32 s40, s37, 0xffffff80
	s_and_b32 s37, s37, 0x7f
	s_lshl_b32 s40, s40, 1
	s_add_u32 s40, s40, s37
	s_add_u32 s40, s40, s41
	s_mul_i32 s40, s40, 0x1000
	s_lshl_b32 s36, s36, 7
	s_add_u32 s40, s40, s36
	s_add_u32 s32, s10, s40
	s_addc_u32 s33, s11, 0
	ds_write_b32 v186, v0 offset:0
	ds_write_b32 v186, v1 offset:4
	ds_write_b32 v186, v2 offset:8
	ds_write_b32 v186, v3 offset:12
	ds_write_b32 v186, v4 offset:1056
	ds_write_b32 v186, v5 offset:1060
	ds_write_b32 v186, v6 offset:1064
	ds_write_b32 v186, v7 offset:1068
	ds_write_b32 v186, v8 offset:2112
	ds_write_b32 v186, v9 offset:2116
	ds_write_b32 v186, v10 offset:2120
	ds_write_b32 v186, v11 offset:2124
	ds_write_b32 v186, v12 offset:3168
	ds_write_b32 v186, v13 offset:3172
	ds_write_b32 v186, v14 offset:3176
	ds_write_b32 v186, v15 offset:3180
	ds_write_b32 v186, v16 offset:4224
	ds_write_b32 v186, v17 offset:4228
	ds_write_b32 v186, v18 offset:4232
	ds_write_b32 v186, v19 offset:4236
	ds_write_b32 v186, v20 offset:5280
	ds_write_b32 v186, v21 offset:5284
	ds_write_b32 v186, v22 offset:5288
	ds_write_b32 v186, v23 offset:5292
	ds_write_b32 v186, v24 offset:6336
	ds_write_b32 v186, v25 offset:6340
	ds_write_b32 v186, v26 offset:6344
	ds_write_b32 v186, v27 offset:6348
	ds_write_b32 v186, v28 offset:7392
	ds_write_b32 v186, v29 offset:7396
	ds_write_b32 v186, v30 offset:7400
	ds_write_b32 v186, v31 offset:7404
	s_waitcnt lgkmcnt(0)
	ds_read2_b32 v[96:97], v187 offset0:0 offset1:8
	ds_read2_b32 v[100:101], v187 offset0:33 offset1:41
	ds_read2_b32 v[104:105], v187 offset0:66 offset1:74
	ds_read2_b32 v[108:109], v187 offset0:99 offset1:107
	ds_read2_b32 v[112:113], v187 offset0:132 offset1:140
	ds_read2_b32 v[116:117], v187 offset0:165 offset1:173
	ds_read2_b32 v[120:121], v187 offset0:198 offset1:206
	ds_read2_b32 v[124:125], v187 offset0:231 offset1:239
	ds_read2_b32 v[98:99], v187 offset0:16 offset1:24
	ds_read2_b32 v[102:103], v187 offset0:49 offset1:57
	ds_read2_b32 v[106:107], v187 offset0:82 offset1:90
	ds_read2_b32 v[110:111], v187 offset0:115 offset1:123
	ds_read2_b32 v[114:115], v187 offset0:148 offset1:156
	ds_read2_b32 v[118:119], v187 offset0:181 offset1:189
	ds_read2_b32 v[122:123], v187 offset0:214 offset1:222
	ds_read2_b32 v[126:127], v187 offset0:247 offset1:255
	s_waitcnt lgkmcnt(0)
	v_mul_f32_e32 v96, v144, v96
	v_mul_f32_e32 v97, v144, v97
	v_mul_f32_e32 v98, v144, v98
	v_mul_f32_e32 v99, v144, v99
	v_mul_f32_e32 v100, v145, v100
	v_mul_f32_e32 v101, v145, v101
	v_mul_f32_e32 v102, v145, v102
	v_mul_f32_e32 v103, v145, v103
	v_mul_f32_e32 v104, v146, v104
	v_mul_f32_e32 v105, v146, v105
	v_mul_f32_e32 v106, v146, v106
	v_mul_f32_e32 v107, v146, v107
	v_mul_f32_e32 v108, v147, v108
	v_mul_f32_e32 v109, v147, v109
	v_mul_f32_e32 v110, v147, v110
	v_mul_f32_e32 v111, v147, v111
	v_mul_f32_e32 v112, v148, v112
	v_mul_f32_e32 v113, v148, v113
	v_mul_f32_e32 v114, v148, v114
	v_mul_f32_e32 v115, v148, v115
	v_mul_f32_e32 v116, v149, v116
	v_mul_f32_e32 v117, v149, v117
	v_mul_f32_e32 v118, v149, v118
	v_mul_f32_e32 v119, v149, v119
	v_mul_f32_e32 v120, v150, v120
	v_mul_f32_e32 v121, v150, v121
	v_mul_f32_e32 v122, v150, v122
	v_mul_f32_e32 v123, v150, v123
	v_mul_f32_e32 v124, v151, v124
	v_mul_f32_e32 v125, v151, v125
	v_mul_f32_e32 v126, v151, v126
	v_mul_f32_e32 v127, v151, v127
	v_cvt_pk_bf16_f32 v128, v96, v100
	v_cvt_pk_bf16_f32 v129, v104, v108
	v_cvt_pk_bf16_f32 v130, v112, v116
	v_cvt_pk_bf16_f32 v131, v120, v124
	global_store_dwordx4 v182, v[128:131], s[32:33]
	v_cvt_pk_bf16_f32 v132, v97, v101
	v_cvt_pk_bf16_f32 v133, v105, v109
	v_cvt_pk_bf16_f32 v134, v113, v117
	v_cvt_pk_bf16_f32 v135, v121, v125
	global_store_dwordx4 v183, v[132:135], s[32:33]
	v_cvt_pk_bf16_f32 v136, v98, v102
	v_cvt_pk_bf16_f32 v137, v106, v110
	v_cvt_pk_bf16_f32 v138, v114, v118
	v_cvt_pk_bf16_f32 v139, v122, v126
	global_store_dwordx4 v184, v[136:139], s[32:33]
	v_cvt_pk_bf16_f32 v140, v99, v103
	v_cvt_pk_bf16_f32 v141, v107, v111
	v_cvt_pk_bf16_f32 v142, v115, v119
	v_cvt_pk_bf16_f32 v143, v123, v127
	global_store_dwordx4 v185, v[140:143], s[32:33]
	s_add_u32 s21, s21, 0x400
	s_cmp_lt_u32 s21, 0x2c00
	s_cbranch_scc0 .Ltr_done_p4up
.Ltr_st1_p4up:
	s_cmp_lt_u32 s20, 0x2c00
	s_cbranch_scc0 .Ltr_nl1_p4up
	s_and_b32 s37, s20, 7
	s_lshr_b32 s36, s20, 3
	s_lshr_b32 s42, s36, 5
	s_mul_hi_u32 s42, s42, 0xba2e8ba3
	s_lshr_b32 s42, s42, 3
	s_mul_i32 s43, s42, 0x160
	s_sub_u32 s36, s36, s43
	s_lshl_b32 s42, s42, 3
	s_add_u32 s42, s42, s37
	s_mov_b32 s37, s36
	s_mov_b32 s36, s42
	s_mul_i32 s40, s36, 0x2c0000
	s_lshl_b32 s37, s37, 7
	s_add_u32 s40, s40, s37
	s_add_u32 s26, s8, s40
	s_addc_u32 s27, s9, 0
	global_load_dwordx4 v[0:3], v171, s[26:27]
	global_load_dwordx4 v[4:7], v172, s[26:27]
	global_load_dwordx4 v[8:11], v173, s[26:27]
	global_load_dwordx4 v[12:15], v174, s[26:27]
	global_load_dwordx4 v[16:19], v175, s[26:27]
	global_load_dwordx4 v[20:23], v177, s[26:27]
	global_load_dwordx4 v[24:27], v180, s[26:27]
	global_load_dwordx4 v[28:31], v181, s[26:27]
	s_lshl_b32 s40, s36, 8
	s_add_u32 s34, s6, s40
	s_addc_u32 s35, s7, 0
	global_load_dwordx4 v[144:147], v188, s[34:35]
	global_load_dwordx4 v[148:151], v188, s[34:35] offset:16
	s_waitcnt vmcnt(20)
	s_branch .Ltr_pr1_p4up

; #define LAS __attribute__((address_space(3)))
; __device__ __forceinline__ unsigned cvtpk(float lo, float hi) { f32x2_t v = {lo, hi}; bf16x2_t b = __builtin_convertvector(v, bf16x2_t); return __builtin_bit_cast(unsigned, b); }
; template <int MODE>
; __device__ __forceinline__ void transpose_item(const float* W, int N, bf16_t* WT, int ldt, int coff, LAS float* scr, int item, int lane, const float* g) {
;     ...
;     for (int i = 0; i < 32; ++i) { const int kk = 2 * i + (lane >> 5); float v = W[(size_t)(k0 + kk) * N + n0 + (lane & 31)]; if (MODE >= 1) v *= g[k0 + kk]; scr[kk * 33 + (lane & 31)] = v; }
;     asm volatile("s_waitcnt lgkmcnt(0)" ::: "memory");
;     const int c = lane & 7;
; #pragma unroll
;     for (int j = 0; j < 4; ++j) {
;         const int n = (lane >> 3) + 8 * j; const LAS float* s = scr + (8 * c) * 33 + n;
;         u32x4 o; o.x = cvtpk(s[0 * 33], s[1 * 33]); o.y = cvtpk(s[2 * 33], s[3 * 33]); o.z = cvtpk(s[4 * 33], s[5 * 33]); o.w = cvtpk(s[6 * 33], s[7 * 33]);
;         int dr = n0 + n;
;         if (MODE == 1) { dr = (dr < DFF) ? 256 * (dr >> 7) + (dr & 127) : 256 * ((dr - DFF) >> 7) + 128 + ((dr - DFF) & 127); }
;         if (MODE == 2) {
;             if (dr >= 6144) { const int t = dr - 6144, ch = t & 2047; dr = 6144 + 256 * (ch >> 7) + ((t >> 11) << 7) + (ch & 127); }
;             else if (dr >= 4096) { const int t = dr - 4096, ch = t & 1023; dr = 4096 + 256 * (ch >> 7) + ((t >> 10) << 7) + (ch & 127); }
;         }
;         *(u32x4*)(WT + (size_t)dr * ldt + coff + k0 + 8 * c) = o;
;     }
.Ltr_pr1_p4up:
	s_add_u32 s20, s20, 0x400
	s_and_b32 s37, s21, 7
	s_lshr_b32 s36, s21, 3
	s_lshr_b32 s42, s36, 5
	s_mul_hi_u32 s42, s42, 0xba2e8ba3
	s_lshr_b32 s42, s42, 3
	s_mul_i32 s43, s42, 0x160
	s_sub_u32 s36, s36, s43
	s_lshl_b32 s42, s42, 3
	s_add_u32 s42, s42, s37
	s_mov_b32 s37, s36
	s_mov_b32 s36, s42
	s_cmp_ge_u32 s37, 0xb0
	s_cselect_b32 s40, 0xb0, 0
	s_cselect_b32 s41, 0x80, 0
	s_sub_u32 s37, s37, s40
	s_lshl_b32 s37, s37, 5
	s_and_b32 s40, s37, 0xffffff80
	s_and_b32 s37, s37, 0x7f
	s_lshl_b32 s40, s40, 1
	s_add_u32 s40, s40, s37
	s_add_u32 s40, s40, s41
	s_mul_i32 s40, s40, 0x1000
	s_lshl_b32 s36, s36, 7
	s_add_u32 s40, s40, s36
	s_add_u32 s32, s10, s40
	s_addc_u32 s33, s11, 0
	ds_write_b32 v186, v32 offset:0
	ds_write_b32 v186, v33 offset:4
	ds_write_b32 v186, v34 offset:8
	ds_write_b32 v186, v35 offset:12
	ds_write_b32 v186, v36 offset:1056
	ds_write_b32 v186, v37 offset:1060
	ds_write_b32 v186, v38 offset:1064
	ds_write_b32 v186, v39 offset:1068
	ds_write_b32 v186, v40 offset:2112
	ds_write_b32 v186, v41 offset:2116
	ds_write_b32 v186, v42 offset:2120
	ds_write_b32 v186, v43 offset:2124
	ds_write_b32 v186, v44 offset:3168
	ds_write_b32 v186, v45 offset:3172
	ds_write_b32 v186, v46 offset:3176
	ds_write_b32 v186, v47 offset:3180
	ds_write_b32 v186, v48 offset:4224
	ds_write_b32 v186, v49 offset:4228
	ds_write_b32 v186, v50 offset:4232
	ds_write_b32 v186, v51 offset:4236
	ds_write_b32 v186, v52 offset:5280
	ds_write_b32 v186, v53 offset:5284
	ds_write_b32 v186, v54 offset:5288
	ds_write_b32 v186, v55 offset:5292
	ds_write_b32 v186, v56 offset:6336
	ds_write_b32 v186, v57 offset:6340
	ds_write_b32 v186, v58 offset:6344
	ds_write_b32 v186, v59 offset:6348
	ds_write_b32 v186, v60 offset:7392
	ds_write_b32 v186, v61 offset:7396
	ds_write_b32 v186, v62 offset:7400
	ds_write_b32 v186, v63 offset:7404
	s_waitcnt lgkmcnt(0)
	ds_read2_b32 v[96:97], v187 offset0:0 offset1:8
	ds_read2_b32 v[100:101], v187 offset0:33 offset1:41
	ds_read2_b32 v[104:105], v187 offset0:66 offset1:74
	ds_read2_b32 v[108:109], v187 offset0:99 offset1:107
	ds_read2_b32 v[112:113], v187 offset0:132 offset1:140
	ds_read2_b32 v[116:117], v187 offset0:165 offset1:173
	ds_read2_b32 v[120:121], v187 offset0:198 offset1:206
	ds_read2_b32 v[124:125], v187 offset0:231 offset1:239
	ds_read2_b32 v[98:99], v187 offset0:16 offset1:24
	ds_read2_b32 v[102:103], v187 offset0:49 offset1:57
	ds_read2_b32 v[106:107], v187 offset0:82 offset1:90
	ds_read2_b32 v[110:111], v187 offset0:115 offset1:123
	ds_read2_b32 v[114:115], v187 offset0:148 offset1:156
	ds_read2_b32 v[118:119], v187 offset0:181 offset1:189
	ds_read2_b32 v[122:123], v187 offset0:214 offset1:222
	ds_read2_b32 v[126:127], v187 offset0:247 offset1:255
	s_waitcnt lgkmcnt(0)
	v_mul_f32_e32 v96, v152, v96
	v_mul_f32_e32 v97, v152, v97
	v_mul_f32_e32 v98, v152, v98
	v_mul_f32_e32 v99, v152, v99
	v_mul_f32_e32 v100, v153, v100
	v_mul_f32_e32 v101, v153, v101
	v_mul_f32_e32 v102, v153, v102
	v_mul_f32_e32 v103, v153, v103
	v_mul_f32_e32 v104, v154, v104
	v_mul_f32_e32 v105, v154, v105
	v_mul_f32_e32 v106, v154, v106
	v_mul_f32_e32 v107, v154, v107
	v_mul_f32_e32 v108, v155, v108
	v_mul_f32_e32 v109, v155, v109
	v_mul_f32_e32 v110, v155, v110
	v_mul_f32_e32 v111, v155, v111
	v_mul_f32_e32 v112, v156, v112
	v_mul_f32_e32 v113, v156, v113
	v_mul_f32_e32 v114, v156, v114
	v_mul_f32_e32 v115, v156, v115
	v_mul_f32_e32 v116, v157, v116
	v_mul_f32_e32 v117, v157, v117
	v_mul_f32_e32 v118, v157, v118
	v_mul_f32_e32 v119, v157, v119
	v_mul_f32_e32 v120, v158, v120
	v_mul_f32_e32 v121, v158, v121
	v_mul_f32_e32 v122, v158, v122
	v_mul_f32_e32 v123, v158, v123
	v_mul_f32_e32 v124, v159, v124
	v_mul_f32_e32 v125, v159, v125
	v_mul_f32_e32 v126, v159, v126
	v_mul_f32_e32 v127, v159, v127
	v_cvt_pk_bf16_f32 v128, v96, v100
	v_cvt_pk_bf16_f32 v129, v104, v108
	v_cvt_pk_bf16_f32 v130, v112, v116
	v_cvt_pk_bf16_f32 v131, v120, v124
	global_store_dwordx4 v182, v[128:131], s[32:33]
	v_cvt_pk_bf16_f32 v132, v97, v101
	v_cvt_pk_bf16_f32 v133, v105, v109
	v_cvt_pk_bf16_f32 v134, v113, v117
	v_cvt_pk_bf16_f32 v135, v121, v125
	global_store_dwordx4 v183, v[132:135], s[32:33]
	v_cvt_pk_bf16_f32 v136, v98, v102
	v_cvt_pk_bf16_f32 v137, v106, v110
	v_cvt_pk_bf16_f32 v138, v114, v118
	v_cvt_pk_bf16_f32 v139, v122, v126
	global_store_dwordx4 v184, v[136:139], s[32:33]
	v_cvt_pk_bf16_f32 v140, v99, v103
	v_cvt_pk_bf16_f32 v141, v107, v111
	v_cvt_pk_bf16_f32 v142, v115, v119
	v_cvt_pk_bf16_f32 v143, v123, v127
	global_store_dwordx4 v185, v[140:143], s[32:33]
	s_add_u32 s21, s21, 0x400
	s_cmp_lt_u32 s21, 0x2c00
	s_cbranch_scc0 .Ltr_done_p4up
.Ltr_st2_p4up:
	s_cmp_lt_u32 s20, 0x2c00
	s_cbranch_scc0 .Ltr_nl2_p4up
	s_and_b32 s37, s20, 7
	s_lshr_b32 s36, s20, 3
	s_lshr_b32 s42, s36, 5
	s_mul_hi_u32 s42, s42, 0xba2e8ba3
	s_lshr_b32 s42, s42, 3
	s_mul_i32 s43, s42, 0x160
	s_sub_u32 s36, s36, s43
	s_lshl_b32 s42, s42, 3
	s_add_u32 s42, s42, s37
	s_mov_b32 s37, s36
	s_mov_b32 s36, s42
	s_mul_i32 s40, s36, 0x2c0000
	s_lshl_b32 s37, s37, 7
	s_add_u32 s40, s40, s37
	s_add_u32 s26, s8, s40
	s_addc_u32 s27, s9, 0
	global_load_dwordx4 v[32:35], v171, s[26:27]
	global_load_dwordx4 v[36:39], v172, s[26:27]
	global_load_dwordx4 v[40:43], v173, s[26:27]
	global_load_dwordx4 v[44:47], v174, s[26:27]
	global_load_dwordx4 v[48:51], v175, s[26:27]
	global_load_dwordx4 v[52:55], v177, s[26:27]
	global_load_dwordx4 v[56:59], v180, s[26:27]
	global_load_dwordx4 v[60:63], v181, s[26:27]
	s_lshl_b32 s40, s36, 8
	s_add_u32 s34, s6, s40
	s_addc_u32 s35, s7, 0
	global_load_dwordx4 v[152:155], v188, s[34:35]
	global_load_dwordx4 v[156:159], v188, s[34:35] offset:16
	s_waitcnt vmcnt(20)
	s_branch .Ltr_pr2_p4up

; #define LAS __attribute__((address_space(3)))
; __device__ __forceinline__ unsigned cvtpk(float lo, float hi) { f32x2_t v = {lo, hi}; bf16x2_t b = __builtin_convertvector(v, bf16x2_t); return __builtin_bit_cast(unsigned, b); }
; template <int MODE>
; __device__ __forceinline__ void transpose_item(const float* W, int N, bf16_t* WT, int ldt, int coff, LAS float* scr, int item, int lane, const float* g) {
;     ...
;     for (int i = 0; i < 32; ++i) { const int kk = 2 * i + (lane >> 5); float v = W[(size_t)(k0 + kk) * N + n0 + (lane & 31)]; if (MODE >= 1) v *= g[k0 + kk]; scr[kk * 33 + (lane & 31)] = v; }
;     asm volatile("s_waitcnt lgkmcnt(0)" ::: "memory");
;     const int c = lane & 7;
; #pragma unroll
;     for (int j = 0; j < 4; ++j) {
;         const int n = (lane >> 3) + 8 * j; const LAS float* s = scr + (8 * c) * 33 + n;
;         u32x4 o; o.x = cvtpk(s[0 * 33], s[1 * 33]); o.y = cvtpk(s[2 * 33], s[3 * 33]); o.z = cvtpk(s[4 * 33], s[5 * 33]); o.w = cvtpk(s[6 * 33], s[7 * 33]);
;         int dr = n0 + n;
;         if (MODE == 1) { dr = (dr < DFF) ? 256 * (dr >> 7) + (dr & 127) : 256 * ((dr - DFF) >> 7) + 128 + ((dr - DFF) & 127); }
;         if (MODE == 2) {
;             if (dr >= 6144) { const int t = dr - 6144, ch = t & 2047; dr = 6144 + 256 * (ch >> 7) + ((t >> 11) << 7) + (ch & 127); }
;             else if (dr >= 4096) { const int t = dr - 4096, ch = t & 1023; dr = 4096 + 256 * (ch >> 7) + ((t >> 10) << 7) + (ch & 127); }
;         }
;         *(u32x4*)(WT + (size_t)dr * ldt + coff + k0 + 8 * c) = o;
;     }
.Ltr_pr2_p4up:
	s_add_u32 s20, s20, 0x400
	s_and_b32 s37, s21, 7
	s_lshr_b32 s36, s21, 3
	s_lshr_b32 s42, s36, 5
	s_mul_hi_u32 s42, s42, 0xba2e8ba3
	s_lshr_b32 s42, s42, 3
	s_mul_i32 s43, s42, 0x160
	s_sub_u32 s36, s36, s43
	s_lshl_b32 s42, s42, 3
	s_add_u32 s42, s42, s37
	s_mov_b32 s37, s36
	s_mov_b32 s36, s42
	s_cmp_ge_u32 s37, 0xb0
	s_cselect_b32 s40, 0xb0, 0
	s_cselect_b32 s41, 0x80, 0
	s_sub_u32 s37, s37, s40
	s_lshl_b32 s37, s37, 5
	s_and_b32 s40, s37, 0xffffff80
	s_and_b32 s37, s37, 0x7f
	s_lshl_b32 s40, s40, 1
	s_add_u32 s40, s40, s37
	s_add_u32 s40, s40, s41
	s_mul_i32 s40, s40, 0x1000
	s_lshl_b32 s36, s36, 7
	s_add_u32 s40, s40, s36
	s_add_u32 s32, s10, s40
	s_addc_u32 s33, s11, 0
	ds_write_b32 v186, v64 offset:0
	ds_write_b32 v186, v65 offset:4
	ds_write_b32 v186, v66 offset:8
	ds_write_b32 v186, v67 offset:12
	ds_write_b32 v186, v68 offset:1056
	ds_write_b32 v186, v69 offset:1060
	ds_write_b32 v186, v70 offset:1064
	ds_write_b32 v186, v71 offset:1068
	ds_write_b32 v186, v72 offset:2112
	ds_write_b32 v186, v73 offset:2116
	ds_write_b32 v186, v74 offset:2120
	ds_write_b32 v186, v75 offset:2124
	ds_write_b32 v186, v76 offset:3168
	ds_write_b32 v186, v77 offset:3172
	ds_write_b32 v186, v78 offset:3176
	ds_write_b32 v186, v79 offset:3180
	ds_write_b32 v186, v80 offset:4224
	ds_write_b32 v186, v81 offset:4228
	ds_write_b32 v186, v82 offset:4232
	ds_write_b32 v186, v83 offset:4236
	ds_write_b32 v186, v84 offset:5280
	ds_write_b32 v186, v85 offset:5284
	ds_write_b32 v186, v86 offset:5288
	ds_write_b32 v186, v87 offset:5292
	ds_write_b32 v186, v88 offset:6336
	ds_write_b32 v186, v89 offset:6340
	ds_write_b32 v186, v90 offset:6344
	ds_write_b32 v186, v91 offset:6348
	ds_write_b32 v186, v92 offset:7392
	ds_write_b32 v186, v93 offset:7396
	ds_write_b32 v186, v94 offset:7400
	ds_write_b32 v186, v95 offset:7404
	s_waitcnt lgkmcnt(0)
	ds_read2_b32 v[96:97], v187 offset0:0 offset1:8
	ds_read2_b32 v[100:101], v187 offset0:33 offset1:41
	ds_read2_b32 v[104:105], v187 offset0:66 offset1:74
	ds_read2_b32 v[108:109], v187 offset0:99 offset1:107
	ds_read2_b32 v[112:113], v187 offset0:132 offset1:140
	ds_read2_b32 v[116:117], v187 offset0:165 offset1:173
	ds_read2_b32 v[120:121], v187 offset0:198 offset1:206
	ds_read2_b32 v[124:125], v187 offset0:231 offset1:239
	ds_read2_b32 v[98:99], v187 offset0:16 offset1:24
	ds_read2_b32 v[102:103], v187 offset0:49 offset1:57
	ds_read2_b32 v[106:107], v187 offset0:82 offset1:90
	ds_read2_b32 v[110:111], v187 offset0:115 offset1:123
	ds_read2_b32 v[114:115], v187 offset0:148 offset1:156
	ds_read2_b32 v[118:119], v187 offset0:181 offset1:189
	ds_read2_b32 v[122:123], v187 offset0:214 offset1:222
	ds_read2_b32 v[126:127], v187 offset0:247 offset1:255
	s_waitcnt lgkmcnt(0)
	v_mul_f32_e32 v96, v160, v96
	v_mul_f32_e32 v97, v160, v97
	v_mul_f32_e32 v98, v160, v98
	v_mul_f32_e32 v99, v160, v99
	v_mul_f32_e32 v100, v161, v100
	v_mul_f32_e32 v101, v161, v101
	v_mul_f32_e32 v102, v161, v102
	v_mul_f32_e32 v103, v161, v103
	v_mul_f32_e32 v104, v162, v104
	v_mul_f32_e32 v105, v162, v105
	v_mul_f32_e32 v106, v162, v106
	v_mul_f32_e32 v107, v162, v107
	v_mul_f32_e32 v108, v163, v108
	v_mul_f32_e32 v109, v163, v109
	v_mul_f32_e32 v110, v163, v110
	v_mul_f32_e32 v111, v163, v111
	v_mul_f32_e32 v112, v164, v112
	v_mul_f32_e32 v113, v164, v113
	v_mul_f32_e32 v114, v164, v114
	v_mul_f32_e32 v115, v164, v115
	v_mul_f32_e32 v116, v165, v116
	v_mul_f32_e32 v117, v165, v117
	v_mul_f32_e32 v118, v165, v118
	v_mul_f32_e32 v119, v165, v119
	v_mul_f32_e32 v120, v166, v120
	v_mul_f32_e32 v121, v166, v121
	v_mul_f32_e32 v122, v166, v122
	v_mul_f32_e32 v123, v166, v123
	v_mul_f32_e32 v124, v167, v124
	v_mul_f32_e32 v125, v167, v125
	v_mul_f32_e32 v126, v167, v126
	v_mul_f32_e32 v127, v167, v127
	v_cvt_pk_bf16_f32 v128, v96, v100
	v_cvt_pk_bf16_f32 v129, v104, v108
	v_cvt_pk_bf16_f32 v130, v112, v116
	v_cvt_pk_bf16_f32 v131, v120, v124
	global_store_dwordx4 v182, v[128:131], s[32:33]
	v_cvt_pk_bf16_f32 v132, v97, v101
	v_cvt_pk_bf16_f32 v133, v105, v109
	v_cvt_pk_bf16_f32 v134, v113, v117
	v_cvt_pk_bf16_f32 v135, v121, v125
	global_store_dwordx4 v183, v[132:135], s[32:33]
	v_cvt_pk_bf16_f32 v136, v98, v102
	v_cvt_pk_bf16_f32 v137, v106, v110
	v_cvt_pk_bf16_f32 v138, v114, v118
	v_cvt_pk_bf16_f32 v139, v122, v126
	global_store_dwordx4 v184, v[136:139], s[32:33]
	v_cvt_pk_bf16_f32 v140, v99, v103
	v_cvt_pk_bf16_f32 v141, v107, v111
	v_cvt_pk_bf16_f32 v142, v115, v119
	v_cvt_pk_bf16_f32 v143, v123, v127
	global_store_dwordx4 v185, v[140:143], s[32:33]
	s_add_u32 s21, s21, 0x400
	s_cmp_lt_u32 s21, 0x2c00
	s_cbranch_scc0 .Ltr_done_p4up
	s_branch .Ltr_st0_p4up

; #define QUARTERS(EPI) if (G == 256 && bx < 128) { Unit qu; S.unit_of(512 + (bx >> 2), qu); qu.ra = ((bx >> 1) & 1) * 128; qu.cb = (bx & 1) * 128; pg8::gemm_quarter<EPI>(lds, g, qu, E); }
; template <class Epi>
; __device__ __forceinline__ void gemm_quarter(LAS unsigned char* lds, const Gemm g, const Unit u, const Epi& E) {
;     const int tid = threadIdx.x, wid = __builtin_amdgcn_readfirstlane(tid >> 6), lane = tid & 63, wr = wid >> 2, wc = wid & 3, fr = lane & 15, fq = lane >> 4;
;     const int K = g.K, nt = K / BK;
;     unsigned voffA[2], voffB[2];
; #pragma unroll
;     for (int i = 0; i < 2; ++i) { int R, C; stage_rc(tid * 16 + i * 8192, R, C); const int Rb = (R & ~31) + perm32(R & 31);
;         voffA[i] = (unsigned)(R * g.lda + C) * 2u; voffB[i] = (unsigned)(Rb * g.ldb + C) * 2u; }
;     const unsigned ldsw = (unsigned)wid * 1024u;
;     const int aoff = lds_byte(wr * 64 + fr, fq * 8), boff = lds_byte(wc * 32 + fr, fq * 8);
; __global__ void __launch_bounds__(512, 2) mk_fwd(Args a) {
;     ...
;         pg8::Gemm g{MERGED, WO, DM, DM, DM}; pg8::StaticOrder S; S.init(MTOT / 256, DM / 256, G, bx, QLIM);
;         Epi4 E{XB, HB, rowss};
;         QUARTERS(Epi4)
.Lp4t_done:
	s_cmpk_lt_i32 s2, 0x80
	v_readlane_b32 s6, v250, 24
	s_cselect_b64 s[0:1], -1, 0
	v_readlane_b32 s7, v250, 25
	s_and_b64 s[0:1], s[0:1], s[6:7]
	v_bfe_u32 v45, v179, 4, 2
	s_and_b64 vcc, exec, s[0:1]
	v_lshlrev_b32_e32 v42, 3, v45
	v_lshlrev_b32_e32 v43, 4, v45
	v_cmp_eq_u32_e64 s[6:7], 0, v45
	s_cbranch_vccnz .LBB0_770
	v_lshrrev_b32_e32 v3, 1, v179
	v_lshrrev_b32_e32 v4, 5, v179
	v_and_b32_e32 v3, 24, v3
	v_and_b32_e32 v4, 4, v4
	v_bfe_u32 v5, v179, 2, 2
	v_lshlrev_b32_e32 v0, 4, v179
	v_and_b32_e32 v1, 32, v179
	v_bfe_u32 v2, v179, 2, 4
	v_or3_b32 v3, v4, v5, v3
	v_lshrrev_b32_e32 v4, 3, v179
	s_movk_i32 s0, 0x70
	v_bitop3_b32 v1, v0, v1, 48 bitop3:0x6c
	v_and_or_b32 v5, v4, s0, v2
	s_movk_i32 s0, 0x60
	v_add_u32_e32 v0, 0x2000, v0
	v_and_or_b32 v4, v4, s0, v3
	v_lshrrev_b32_e32 v0, 7, v0
	s_movk_i32 s0, 0xf0
	v_and_or_b32 v2, v0, s0, v2
	s_movk_i32 s0, 0xe0
	v_and_or_b32 v1, v179, 64, v1
	v_and_or_b32 v0, v0, s0, v3
	v_lshl_or_b32 v128, v5, 12, v1
	v_lshl_or_b32 v130, v4, 12, v1
	v_lshl_or_b32 v132, v2, 12, v1
	v_lshl_or_b32 v134, v0, 12, v1
	v_lshlrev_b32_e32 v0, 6, v179
	v_lshlrev_b32_e32 v1, 2, v179
	v_lshlrev_b32_e32 v9, 4, v45
	v_and_b32_e32 v0, 0x3c0, v0
	v_and_b32_e32 v1, 32, v1
	v_and_b32_e32 v40, 15, v179
	v_lshlrev_b32_e32 v8, 3, v45
	v_bitop3_b32 v41, v9, v1, v0 bitop3:0x36
	s_cbranch_execz .LBB0_771
	s_branch .LBB0_796

; #define LAS __attribute__((address_space(3)))
; __device__ __forceinline__ unsigned cvtpk(float lo, float hi) { f32x2_t v = {lo, hi}; bf16x2_t b = __builtin_convertvector(v, bf16x2_t); return __builtin_bit_cast(unsigned, b); }
; #define PG8_WAIT_V(n) asm volatile("s_waitcnt vmcnt(" #n ")" ::: "memory")
; #define PG8_BAR __builtin_amdgcn_s_barrier()
; template <class Epi>
; __device__ __forceinline__ void gemm_phase(LAS unsigned char* lds, const Gemm g, const StaticOrder& S, const Epi& E) {
;     ...
;     PG8_WAIT_V(0);
;     PG8_BAR;
; template <int MODE>
; __device__ __forceinline__ void transpose_item(const float* W, int N, bf16_t* WT, int ldt, int coff, LAS float* scr, int item, int lane, const float* g) {
;     const int nblk = N / 32, kb = item / nblk, nb = item % nblk, k0 = 64 * kb, n0 = 32 * nb;
; #pragma unroll 8
;     for (int i = 0; i < 32; ++i) { const int kk = 2 * i + (lane >> 5); float v = W[(size_t)(k0 + kk) * N + n0 + (lane & 31)]; if (MODE >= 1) v *= g[k0 + kk]; scr[kk * 33 + (lane & 31)] = v; }
;     asm volatile("s_waitcnt lgkmcnt(0)" ::: "memory");
;     const int c = lane & 7;
; #pragma unroll
;     for (int j = 0; j < 4; ++j) {
;         const int n = (lane >> 3) + 8 * j; const LAS float* s = scr + (8 * c) * 33 + n;
;         u32x4 o; o.x = cvtpk(s[0 * 33], s[1 * 33]); o.y = cvtpk(s[2 * 33], s[3 * 33]); o.z = cvtpk(s[4 * 33], s[5 * 33]); o.w = cvtpk(s[6 * 33], s[7 * 33]);
.LBB0_978:
	s_waitcnt vmcnt(0)
	v_readlane_b32 s96, v250, 16
	v_readlane_b32 s80, v250, 10
	v_readlane_b32 s14, v250, 28
	v_readlane_b32 s97, v250, 17
	v_readlane_b32 s81, v250, 11
	v_readlane_b32 s88, v250, 5
	v_readlane_b32 s15, v250, 29
	s_barrier
	s_cmp_eq_u32 s3, 0x100
	s_cbranch_scc0 .Lp5t_done
	s_cmp_ge_u32 s2, 0xb0
	s_cbranch_scc0 .Lp5t_done
	v_readlane_b32 s0, v250, 0
	v_readlane_b32 s1, v250, 1
	s_nop 3
	s_sub_u32 s0, s0, 0xd0
	s_subb_u32 s1, s1, 0
	s_load_dwordx2 s[4:5], s[0:1], 0xa8
	s_add_u32 s6, s68, 0x1db00000
	s_addc_u32 s7, s69, 0
	s_lshl_b32 s8, s2, 3
	v_readfirstlane_b32 s9, v179
	s_nop 3
	s_lshr_b32 s9, s9, 6
	s_add_u32 s8, s8, s9
	s_sub_u32 s8, s8, 0x580
	s_lshl_b32 s9, s9, 14
	s_waitcnt lgkmcnt(0)
	s_cmp_lt_u32 s8, 0x1600
	s_cbranch_scc0 .Ltr_done_p5dn
	v_lshrrev_b32_e32 v144, 3, v220
	v_and_b32_e32 v145, 7, v220
	v_mul_u32_u24_e32 v146, 0x2000, v144
	v_lshl_add_u32 v147, v145, 4, v146
	v_add_u32_e32 v148, 0x10000, v147
	v_add_u32_e32 v149, 0x20000, v147
	v_add_u32_e32 v150, 0x30000, v147
	v_add_u32_e32 v151, 0x40000, v147
	v_add_u32_e32 v152, 0x50000, v147
	v_add_u32_e32 v153, 0x60000, v147
	v_add_u32_e32 v154, 0x70000, v147
	v_mul_u32_u24_e32 v146, 0x84, v144
	v_lshl_add_u32 v146, v145, 4, v146
	v_add_u32_e32 v159, s9, v146
	v_mul_u32_u24_e32 v146, 0x420, v145
	v_lshl_add_u32 v146, v144, 2, v146
	v_add_u32_e32 v160, s9, v146
	v_mul_u32_u24_e32 v146, 0x2c00, v144
	v_lshl_add_u32 v155, v145, 4, v146
	v_add_u32_e32 v156, 0x16000, v155
	v_add_u32_e32 v157, 0x2c000, v155
	v_add_u32_e32 v158, 0x42000, v155
	s_mov_b32 s11, s8
	s_mov_b32 s10, s8
	s_and_b32 s36, s10, 7
	s_lshr_b32 s22, s10, 3
	s_lshr_b32 s42, s22, 6
	s_and_b32 s22, s22, 0x3f
	s_lshl_b32 s42, s42, 3
	s_add_u32 s42, s42, s36
	s_mov_b32 s36, s22
	s_mov_b32 s22, s42
	s_mul_i32 s37, s22, 0x80000
	s_lshl_b32 s36, s36, 7
	s_add_u32 s37, s37, s36
	s_add_u32 s32, s4, s37
	s_addc_u32 s33, s5, 0
	global_load_dwordx4 v[0:3], v147, s[32:33]
	global_load_dwordx4 v[4:7], v148, s[32:33]
	global_load_dwordx4 v[8:11], v149, s[32:33]
	global_load_dwordx4 v[12:15], v150, s[32:33]
	global_load_dwordx4 v[16:19], v151, s[32:33]
	global_load_dwordx4 v[20:23], v152, s[32:33]
	global_load_dwordx4 v[24:27], v153, s[32:33]
	global_load_dwordx4 v[28:31], v154, s[32:33]
	s_add_u32 s10, s10, 0x280
	s_cmp_lt_u32 s10, 0x1600
	s_cbranch_scc0 .Ltr_p1_p5dn
	s_and_b32 s36, s10, 7
	s_lshr_b32 s22, s10, 3
	s_lshr_b32 s42, s22, 6
	s_and_b32 s22, s22, 0x3f
	s_lshl_b32 s42, s42, 3
	s_add_u32 s42, s42, s36
	s_mov_b32 s36, s22
	s_mov_b32 s22, s42
	s_mul_i32 s37, s22, 0x80000
	s_lshl_b32 s36, s36, 7
	s_add_u32 s37, s37, s36
	s_add_u32 s32, s4, s37
	s_addc_u32 s33, s5, 0
	global_load_dwordx4 v[32:35], v147, s[32:33]
	global_load_dwordx4 v[36:39], v148, s[32:33]
	global_load_dwordx4 v[40:43], v149, s[32:33]
	global_load_dwordx4 v[44:47], v150, s[32:33]
	global_load_dwordx4 v[48:51], v151, s[32:33]
	global_load_dwordx4 v[52:55], v152, s[32:33]
	global_load_dwordx4 v[56:59], v153, s[32:33]
	global_load_dwordx4 v[60:63], v154, s[32:33]
.Ltr_p1_p5dn:
	s_add_u32 s10, s10, 0x280
.Ltr_st0_p5dn:
	s_cmp_lt_u32 s10, 0x1600
	s_cbranch_scc0 .Ltr_nl0_p5dn
	s_and_b32 s36, s10, 7
	s_lshr_b32 s22, s10, 3
	s_lshr_b32 s42, s22, 6
	s_and_b32 s22, s22, 0x3f
	s_lshl_b32 s42, s42, 3
	s_add_u32 s42, s42, s36
	s_mov_b32 s36, s22
	s_mov_b32 s22, s42
	s_mul_i32 s37, s22, 0x80000
	s_lshl_b32 s36, s36, 7
	s_add_u32 s37, s37, s36
	s_add_u32 s32, s4, s37
	s_addc_u32 s33, s5, 0
	global_load_dwordx4 v[64:67], v147, s[32:33]
	global_load_dwordx4 v[68:71], v148, s[32:33]
	global_load_dwordx4 v[72:75], v149, s[32:33]
	global_load_dwordx4 v[76:79], v150, s[32:33]
	global_load_dwordx4 v[80:83], v151, s[32:33]
	global_load_dwordx4 v[84:87], v152, s[32:33]
	global_load_dwordx4 v[88:91], v153, s[32:33]
	global_load_dwordx4 v[92:95], v154, s[32:33]
	s_waitcnt vmcnt(16)
	s_branch .Ltr_pr0_p5dn
.Ltr_nl0_p5dn:
	s_sub_u32 s22, s10, 0x280
	s_cmp_lt_u32 s22, 0x1600
	s_cbranch_scc0 .Ltr_w00_p5dn
	s_waitcnt vmcnt(8)
	s_branch .Ltr_pr0_p5dn

; #define LAS __attribute__((address_space(3)))
; __device__ __forceinline__ unsigned cvtpk(float lo, float hi) { f32x2_t v = {lo, hi}; bf16x2_t b = __builtin_convertvector(v, bf16x2_t); return __builtin_bit_cast(unsigned, b); }
; template <int MODE>
; __device__ __forceinline__ void transpose_item(const float* W, int N, bf16_t* WT, int ldt, int coff, LAS float* scr, int item, int lane, const float* g) {
;     ...
;     for (int i = 0; i < 32; ++i) { const int kk = 2 * i + (lane >> 5); float v = W[(size_t)(k0 + kk) * N + n0 + (lane & 31)]; if (MODE >= 1) v *= g[k0 + kk]; scr[kk * 33 + (lane & 31)] = v; }
;     asm volatile("s_waitcnt lgkmcnt(0)" ::: "memory");
;     const int c = lane & 7;
; #pragma unroll
;     for (int j = 0; j < 4; ++j) {
;         const int n = (lane >> 3) + 8 * j; const LAS float* s = scr + (8 * c) * 33 + n;
;         u32x4 o; o.x = cvtpk(s[0 * 33], s[1 * 33]); o.y = cvtpk(s[2 * 33], s[3 * 33]); o.z = cvtpk(s[4 * 33], s[5 * 33]); o.w = cvtpk(s[6 * 33], s[7 * 33]);
;         int dr = n0 + n;
;         if (MODE == 1) { dr = (dr < DFF) ? 256 * (dr >> 7) + (dr & 127) : 256 * ((dr - DFF) >> 7) + 128 + ((dr - DFF) & 127); }
;         if (MODE == 2) {
;             if (dr >= 6144) { const int t = dr - 6144, ch = t & 2047; dr = 6144 + 256 * (ch >> 7) + ((t >> 11) << 7) + (ch & 127); }
;             else if (dr >= 4096) { const int t = dr - 4096, ch = t & 1023; dr = 4096 + 256 * (ch >> 7) + ((t >> 10) << 7) + (ch & 127); }
;         }
;         *(u32x4*)(WT + (size_t)dr * ldt + coff + k0 + 8 * c) = o;
.Ltr_pr0_p5dn:
	s_add_u32 s10, s10, 0x280
	s_and_b32 s36, s11, 7
	s_lshr_b32 s22, s11, 3
	s_lshr_b32 s42, s22, 6
	s_and_b32 s22, s22, 0x3f
	s_lshl_b32 s42, s42, 3
	s_add_u32 s42, s42, s36
	s_mov_b32 s36, s22
	s_mov_b32 s22, s42
	s_mul_i32 s37, s36, 0x58000
	s_lshl_b32 s22, s22, 7
	s_add_u32 s37, s37, s22
	s_add_u32 s34, s6, s37
	s_addc_u32 s35, s7, 0
	ds_write_b32 v159, v0 offset:0
	ds_write_b32 v159, v1 offset:4
	ds_write_b32 v159, v2 offset:8
	ds_write_b32 v159, v3 offset:12
	ds_write_b32 v159, v4 offset:1056
	ds_write_b32 v159, v5 offset:1060
	ds_write_b32 v159, v6 offset:1064
	ds_write_b32 v159, v7 offset:1068
	ds_write_b32 v159, v8 offset:2112
	ds_write_b32 v159, v9 offset:2116
	ds_write_b32 v159, v10 offset:2120
	ds_write_b32 v159, v11 offset:2124
	ds_write_b32 v159, v12 offset:3168
	ds_write_b32 v159, v13 offset:3172
	ds_write_b32 v159, v14 offset:3176
	ds_write_b32 v159, v15 offset:3180
	ds_write_b32 v159, v16 offset:4224
	ds_write_b32 v159, v17 offset:4228
	ds_write_b32 v159, v18 offset:4232
	ds_write_b32 v159, v19 offset:4236
	ds_write_b32 v159, v20 offset:5280
	ds_write_b32 v159, v21 offset:5284
	ds_write_b32 v159, v22 offset:5288
	ds_write_b32 v159, v23 offset:5292
	ds_write_b32 v159, v24 offset:6336
	ds_write_b32 v159, v25 offset:6340
	ds_write_b32 v159, v26 offset:6344
	ds_write_b32 v159, v27 offset:6348
	ds_write_b32 v159, v28 offset:7392
	ds_write_b32 v159, v29 offset:7396
	ds_write_b32 v159, v30 offset:7400
	ds_write_b32 v159, v31 offset:7404
	s_waitcnt lgkmcnt(0)
	ds_read2_b32 v[96:97], v160 offset0:0 offset1:8
	ds_read2_b32 v[100:101], v160 offset0:33 offset1:41
	ds_read2_b32 v[104:105], v160 offset0:66 offset1:74
	ds_read2_b32 v[108:109], v160 offset0:99 offset1:107
	ds_read2_b32 v[112:113], v160 offset0:132 offset1:140
	ds_read2_b32 v[116:117], v160 offset0:165 offset1:173
	ds_read2_b32 v[120:121], v160 offset0:198 offset1:206
	ds_read2_b32 v[124:125], v160 offset0:231 offset1:239
	ds_read2_b32 v[98:99], v160 offset0:16 offset1:24
	ds_read2_b32 v[102:103], v160 offset0:49 offset1:57
	ds_read2_b32 v[106:107], v160 offset0:82 offset1:90
	ds_read2_b32 v[110:111], v160 offset0:115 offset1:123
	ds_read2_b32 v[114:115], v160 offset0:148 offset1:156
	ds_read2_b32 v[118:119], v160 offset0:181 offset1:189
	ds_read2_b32 v[122:123], v160 offset0:214 offset1:222
	ds_read2_b32 v[126:127], v160 offset0:247 offset1:255
	s_waitcnt lgkmcnt(0)
	v_cvt_pk_bf16_f32 v128, v96, v100
	v_cvt_pk_bf16_f32 v129, v104, v108
	v_cvt_pk_bf16_f32 v130, v112, v116
	v_cvt_pk_bf16_f32 v131, v120, v124
	global_store_dwordx4 v155, v[128:131], s[34:35]
	v_cvt_pk_bf16_f32 v132, v97, v101
	v_cvt_pk_bf16_f32 v133, v105, v109
	v_cvt_pk_bf16_f32 v134, v113, v117
	v_cvt_pk_bf16_f32 v135, v121, v125
	global_store_dwordx4 v156, v[132:135], s[34:35]
	v_cvt_pk_bf16_f32 v136, v98, v102
	v_cvt_pk_bf16_f32 v137, v106, v110
	v_cvt_pk_bf16_f32 v138, v114, v118
	v_cvt_pk_bf16_f32 v139, v122, v126
	global_store_dwordx4 v157, v[136:139], s[34:35]
	v_cvt_pk_bf16_f32 v140, v99, v103
	v_cvt_pk_bf16_f32 v141, v107, v111
	v_cvt_pk_bf16_f32 v142, v115, v119
	v_cvt_pk_bf16_f32 v143, v123, v127
	global_store_dwordx4 v158, v[140:143], s[34:35]
	s_add_u32 s11, s11, 0x280
	s_cmp_lt_u32 s11, 0x1600
	s_cbranch_scc0 .Ltr_done_p5dn
.Ltr_st1_p5dn:
	s_cmp_lt_u32 s10, 0x1600
	s_cbranch_scc0 .Ltr_nl1_p5dn
	s_and_b32 s36, s10, 7
	s_lshr_b32 s22, s10, 3
	s_lshr_b32 s42, s22, 6
	s_and_b32 s22, s22, 0x3f
	s_lshl_b32 s42, s42, 3
	s_add_u32 s42, s42, s36
	s_mov_b32 s36, s22
	s_mov_b32 s22, s42
	s_mul_i32 s37, s22, 0x80000
	s_lshl_b32 s36, s36, 7
	s_add_u32 s37, s37, s36
	s_add_u32 s32, s4, s37
	s_addc_u32 s33, s5, 0
	global_load_dwordx4 v[0:3], v147, s[32:33]
	global_load_dwordx4 v[4:7], v148, s[32:33]
	global_load_dwordx4 v[8:11], v149, s[32:33]
	global_load_dwordx4 v[12:15], v150, s[32:33]
	global_load_dwordx4 v[16:19], v151, s[32:33]
	global_load_dwordx4 v[20:23], v152, s[32:33]
	global_load_dwordx4 v[24:27], v153, s[32:33]
	global_load_dwordx4 v[28:31], v154, s[32:33]
	s_waitcnt vmcnt(16)
	s_branch .Ltr_pr1_p5dn

; #define LAS __attribute__((address_space(3)))
; __device__ __forceinline__ unsigned cvtpk(float lo, float hi) { f32x2_t v = {lo, hi}; bf16x2_t b = __builtin_convertvector(v, bf16x2_t); return __builtin_bit_cast(unsigned, b); }
; template <int MODE>
; __device__ __forceinline__ void transpose_item(const float* W, int N, bf16_t* WT, int ldt, int coff, LAS float* scr, int item, int lane, const float* g) {
;     ...
;     for (int i = 0; i < 32; ++i) { const int kk = 2 * i + (lane >> 5); float v = W[(size_t)(k0 + kk) * N + n0 + (lane & 31)]; if (MODE >= 1) v *= g[k0 + kk]; scr[kk * 33 + (lane & 31)] = v; }
;     asm volatile("s_waitcnt lgkmcnt(0)" ::: "memory");
;     const int c = lane & 7;
; #pragma unroll
;     for (int j = 0; j < 4; ++j) {
;         const int n = (lane >> 3) + 8 * j; const LAS float* s = scr + (8 * c) * 33 + n;
;         u32x4 o; o.x = cvtpk(s[0 * 33], s[1 * 33]); o.y = cvtpk(s[2 * 33], s[3 * 33]); o.z = cvtpk(s[4 * 33], s[5 * 33]); o.w = cvtpk(s[6 * 33], s[7 * 33]);
;         int dr = n0 + n;
;         if (MODE == 1) { dr = (dr < DFF) ? 256 * (dr >> 7) + (dr & 127) : 256 * ((dr - DFF) >> 7) + 128 + ((dr - DFF) & 127); }
;         if (MODE == 2) {
;             if (dr >= 6144) { const int t = dr - 6144, ch = t & 2047; dr = 6144 + 256 * (ch >> 7) + ((t >> 11) << 7) + (ch & 127); }
;             else if (dr >= 4096) { const int t = dr - 4096, ch = t & 1023; dr = 4096 + 256 * (ch >> 7) + ((t >> 10) << 7) + (ch & 127); }
;         }
;         *(u32x4*)(WT + (size_t)dr * ldt + coff + k0 + 8 * c) = o;
.Ltr_pr1_p5dn:
	s_add_u32 s10, s10, 0x280
	s_and_b32 s36, s11, 7
	s_lshr_b32 s22, s11, 3
	s_lshr_b32 s42, s22, 6
	s_and_b32 s22, s22, 0x3f
	s_lshl_b32 s42, s42, 3
	s_add_u32 s42, s42, s36
	s_mov_b32 s36, s22
	s_mov_b32 s22, s42
	s_mul_i32 s37, s36, 0x58000
	s_lshl_b32 s22, s22, 7
	s_add_u32 s37, s37, s22
	s_add_u32 s34, s6, s37
	s_addc_u32 s35, s7, 0
	ds_write_b32 v159, v32 offset:0
	ds_write_b32 v159, v33 offset:4
	ds_write_b32 v159, v34 offset:8
	ds_write_b32 v159, v35 offset:12
	ds_write_b32 v159, v36 offset:1056
	ds_write_b32 v159, v37 offset:1060
	ds_write_b32 v159, v38 offset:1064
	ds_write_b32 v159, v39 offset:1068
	ds_write_b32 v159, v40 offset:2112
	ds_write_b32 v159, v41 offset:2116
	ds_write_b32 v159, v42 offset:2120
	ds_write_b32 v159, v43 offset:2124
	ds_write_b32 v159, v44 offset:3168
	ds_write_b32 v159, v45 offset:3172
	ds_write_b32 v159, v46 offset:3176
	ds_write_b32 v159, v47 offset:3180
	ds_write_b32 v159, v48 offset:4224
	ds_write_b32 v159, v49 offset:4228
	ds_write_b32 v159, v50 offset:4232
	ds_write_b32 v159, v51 offset:4236
	ds_write_b32 v159, v52 offset:5280
	ds_write_b32 v159, v53 offset:5284
	ds_write_b32 v159, v54 offset:5288
	ds_write_b32 v159, v55 offset:5292
	ds_write_b32 v159, v56 offset:6336
	ds_write_b32 v159, v57 offset:6340
	ds_write_b32 v159, v58 offset:6344
	ds_write_b32 v159, v59 offset:6348
	ds_write_b32 v159, v60 offset:7392
	ds_write_b32 v159, v61 offset:7396
	ds_write_b32 v159, v62 offset:7400
	ds_write_b32 v159, v63 offset:7404
	s_waitcnt lgkmcnt(0)
	ds_read2_b32 v[96:97], v160 offset0:0 offset1:8
	ds_read2_b32 v[100:101], v160 offset0:33 offset1:41
	ds_read2_b32 v[104:105], v160 offset0:66 offset1:74
	ds_read2_b32 v[108:109], v160 offset0:99 offset1:107
	ds_read2_b32 v[112:113], v160 offset0:132 offset1:140
	ds_read2_b32 v[116:117], v160 offset0:165 offset1:173
	ds_read2_b32 v[120:121], v160 offset0:198 offset1:206
	ds_read2_b32 v[124:125], v160 offset0:231 offset1:239
	ds_read2_b32 v[98:99], v160 offset0:16 offset1:24
	ds_read2_b32 v[102:103], v160 offset0:49 offset1:57
	ds_read2_b32 v[106:107], v160 offset0:82 offset1:90
	ds_read2_b32 v[110:111], v160 offset0:115 offset1:123
	ds_read2_b32 v[114:115], v160 offset0:148 offset1:156
	ds_read2_b32 v[118:119], v160 offset0:181 offset1:189
	ds_read2_b32 v[122:123], v160 offset0:214 offset1:222
	ds_read2_b32 v[126:127], v160 offset0:247 offset1:255
	s_waitcnt lgkmcnt(0)
	v_cvt_pk_bf16_f32 v128, v96, v100
	v_cvt_pk_bf16_f32 v129, v104, v108
	v_cvt_pk_bf16_f32 v130, v112, v116
	v_cvt_pk_bf16_f32 v131, v120, v124
	global_store_dwordx4 v155, v[128:131], s[34:35]
	v_cvt_pk_bf16_f32 v132, v97, v101
	v_cvt_pk_bf16_f32 v133, v105, v109
	v_cvt_pk_bf16_f32 v134, v113, v117
	v_cvt_pk_bf16_f32 v135, v121, v125
	global_store_dwordx4 v156, v[132:135], s[34:35]
	v_cvt_pk_bf16_f32 v136, v98, v102
	v_cvt_pk_bf16_f32 v137, v106, v110
	v_cvt_pk_bf16_f32 v138, v114, v118
	v_cvt_pk_bf16_f32 v139, v122, v126
	global_store_dwordx4 v157, v[136:139], s[34:35]
	v_cvt_pk_bf16_f32 v140, v99, v103
	v_cvt_pk_bf16_f32 v141, v107, v111
	v_cvt_pk_bf16_f32 v142, v115, v119
	v_cvt_pk_bf16_f32 v143, v123, v127
	global_store_dwordx4 v158, v[140:143], s[34:35]
	s_add_u32 s11, s11, 0x280
	s_cmp_lt_u32 s11, 0x1600
	s_cbranch_scc0 .Ltr_done_p5dn
.Ltr_st2_p5dn:
	s_cmp_lt_u32 s10, 0x1600
	s_cbranch_scc0 .Ltr_nl2_p5dn
	s_and_b32 s36, s10, 7
	s_lshr_b32 s22, s10, 3
	s_lshr_b32 s42, s22, 6
	s_and_b32 s22, s22, 0x3f
	s_lshl_b32 s42, s42, 3
	s_add_u32 s42, s42, s36
	s_mov_b32 s36, s22
	s_mov_b32 s22, s42
	s_mul_i32 s37, s22, 0x80000
	s_lshl_b32 s36, s36, 7
	s_add_u32 s37, s37, s36
	s_add_u32 s32, s4, s37
	s_addc_u32 s33, s5, 0
	global_load_dwordx4 v[32:35], v147, s[32:33]
	global_load_dwordx4 v[36:39], v148, s[32:33]
	global_load_dwordx4 v[40:43], v149, s[32:33]
	global_load_dwordx4 v[44:47], v150, s[32:33]
	global_load_dwordx4 v[48:51], v151, s[32:33]
	global_load_dwordx4 v[52:55], v152, s[32:33]
	global_load_dwordx4 v[56:59], v153, s[32:33]
	global_load_dwordx4 v[60:63], v154, s[32:33]
	s_waitcnt vmcnt(16)
	s_branch .Ltr_pr2_p5dn

; #define LAS __attribute__((address_space(3)))
; __device__ __forceinline__ unsigned cvtpk(float lo, float hi) { f32x2_t v = {lo, hi}; bf16x2_t b = __builtin_convertvector(v, bf16x2_t); return __builtin_bit_cast(unsigned, b); }
; template <int MODE>
; __device__ __forceinline__ void transpose_item(const float* W, int N, bf16_t* WT, int ldt, int coff, LAS float* scr, int item, int lane, const float* g) {
;     ...
;     for (int i = 0; i < 32; ++i) { const int kk = 2 * i + (lane >> 5); float v = W[(size_t)(k0 + kk) * N + n0 + (lane & 31)]; if (MODE >= 1) v *= g[k0 + kk]; scr[kk * 33 + (lane & 31)] = v; }
;     asm volatile("s_waitcnt lgkmcnt(0)" ::: "memory");
;     const int c = lane & 7;
; #pragma unroll
;     for (int j = 0; j < 4; ++j) {
;         const int n = (lane >> 3) + 8 * j; const LAS float* s = scr + (8 * c) * 33 + n;
;         u32x4 o; o.x = cvtpk(s[0 * 33], s[1 * 33]); o.y = cvtpk(s[2 * 33], s[3 * 33]); o.z = cvtpk(s[4 * 33], s[5 * 33]); o.w = cvtpk(s[6 * 33], s[7 * 33]);
;         int dr = n0 + n;
;         if (MODE == 1) { dr = (dr < DFF) ? 256 * (dr >> 7) + (dr & 127) : 256 * ((dr - DFF) >> 7) + 128 + ((dr - DFF) & 127); }
;         if (MODE == 2) {
;             if (dr >= 6144) { const int t = dr - 6144, ch = t & 2047; dr = 6144 + 256 * (ch >> 7) + ((t >> 11) << 7) + (ch & 127); }
;             else if (dr >= 4096) { const int t = dr - 4096, ch = t & 1023; dr = 4096 + 256 * (ch >> 7) + ((t >> 10) << 7) + (ch & 127); }
;         }
;         *(u32x4*)(WT + (size_t)dr * ldt + coff + k0 + 8 * c) = o;
.Ltr_pr2_p5dn:
	s_add_u32 s10, s10, 0x280
	s_and_b32 s36, s11, 7
	s_lshr_b32 s22, s11, 3
	s_lshr_b32 s42, s22, 6
	s_and_b32 s22, s22, 0x3f
	s_lshl_b32 s42, s42, 3
	s_add_u32 s42, s42, s36
	s_mov_b32 s36, s22
	s_mov_b32 s22, s42
	s_mul_i32 s37, s36, 0x58000
	s_lshl_b32 s22, s22, 7
	s_add_u32 s37, s37, s22
	s_add_u32 s34, s6, s37
	s_addc_u32 s35, s7, 0
	ds_write_b32 v159, v64 offset:0
	ds_write_b32 v159, v65 offset:4
	ds_write_b32 v159, v66 offset:8
	ds_write_b32 v159, v67 offset:12
	ds_write_b32 v159, v68 offset:1056
	ds_write_b32 v159, v69 offset:1060
	ds_write_b32 v159, v70 offset:1064
	ds_write_b32 v159, v71 offset:1068
	ds_write_b32 v159, v72 offset:2112
	ds_write_b32 v159, v73 offset:2116
	ds_write_b32 v159, v74 offset:2120
	ds_write_b32 v159, v75 offset:2124
	ds_write_b32 v159, v76 offset:3168
	ds_write_b32 v159, v77 offset:3172
	ds_write_b32 v159, v78 offset:3176
	ds_write_b32 v159, v79 offset:3180
	ds_write_b32 v159, v80 offset:4224
	ds_write_b32 v159, v81 offset:4228
	ds_write_b32 v159, v82 offset:4232
	ds_write_b32 v159, v83 offset:4236
	ds_write_b32 v159, v84 offset:5280
	ds_write_b32 v159, v85 offset:5284
	ds_write_b32 v159, v86 offset:5288
	ds_write_b32 v159, v87 offset:5292
	ds_write_b32 v159, v88 offset:6336
	ds_write_b32 v159, v89 offset:6340
	ds_write_b32 v159, v90 offset:6344
	ds_write_b32 v159, v91 offset:6348
	ds_write_b32 v159, v92 offset:7392
	ds_write_b32 v159, v93 offset:7396
	ds_write_b32 v159, v94 offset:7400
	ds_write_b32 v159, v95 offset:7404
	s_waitcnt lgkmcnt(0)
	ds_read2_b32 v[96:97], v160 offset0:0 offset1:8
	ds_read2_b32 v[100:101], v160 offset0:33 offset1:41
	ds_read2_b32 v[104:105], v160 offset0:66 offset1:74
	ds_read2_b32 v[108:109], v160 offset0:99 offset1:107
	ds_read2_b32 v[112:113], v160 offset0:132 offset1:140
	ds_read2_b32 v[116:117], v160 offset0:165 offset1:173
	ds_read2_b32 v[120:121], v160 offset0:198 offset1:206
	ds_read2_b32 v[124:125], v160 offset0:231 offset1:239
	ds_read2_b32 v[98:99], v160 offset0:16 offset1:24
	ds_read2_b32 v[102:103], v160 offset0:49 offset1:57
	ds_read2_b32 v[106:107], v160 offset0:82 offset1:90
	ds_read2_b32 v[110:111], v160 offset0:115 offset1:123
	ds_read2_b32 v[114:115], v160 offset0:148 offset1:156
	ds_read2_b32 v[118:119], v160 offset0:181 offset1:189
	ds_read2_b32 v[122:123], v160 offset0:214 offset1:222
	ds_read2_b32 v[126:127], v160 offset0:247 offset1:255
	s_waitcnt lgkmcnt(0)
	v_cvt_pk_bf16_f32 v128, v96, v100
	v_cvt_pk_bf16_f32 v129, v104, v108
	v_cvt_pk_bf16_f32 v130, v112, v116
	v_cvt_pk_bf16_f32 v131, v120, v124
	global_store_dwordx4 v155, v[128:131], s[34:35]
	v_cvt_pk_bf16_f32 v132, v97, v101
	v_cvt_pk_bf16_f32 v133, v105, v109
	v_cvt_pk_bf16_f32 v134, v113, v117
	v_cvt_pk_bf16_f32 v135, v121, v125
	global_store_dwordx4 v156, v[132:135], s[34:35]
	v_cvt_pk_bf16_f32 v136, v98, v102
	v_cvt_pk_bf16_f32 v137, v106, v110
	v_cvt_pk_bf16_f32 v138, v114, v118
	v_cvt_pk_bf16_f32 v139, v122, v126
	global_store_dwordx4 v157, v[136:139], s[34:35]
	v_cvt_pk_bf16_f32 v140, v99, v103
	v_cvt_pk_bf16_f32 v141, v107, v111
	v_cvt_pk_bf16_f32 v142, v115, v119
	v_cvt_pk_bf16_f32 v143, v123, v127
	global_store_dwordx4 v158, v[140:143], s[34:35]
	s_add_u32 s11, s11, 0x280
	s_cmp_lt_u32 s11, 0x1600
	s_cbranch_scc0 .Ltr_done_p5dn
	s_branch .Ltr_st0_p5dn

; __device__ __forceinline__ unsigned xb_ld(unsigned* p)              { return __hip_atomic_load(p, __ATOMIC_RELAXED, __HIP_MEMORY_SCOPE_AGENT); }
; __device__ __forceinline__ void xcd_barrier_complete(unsigned* bar, unsigned x, unsigned& nloc, unsigned& nx) {
;     const unsigned G = gridDim.x * gridDim.y * gridDim.z;
;     unsigned sum, cnt, mine, sp = 0u;
;     for (;;) {
;         sum = 0u; cnt = 0u; mine = 0u;
; #pragma unroll
;         for (unsigned j = 0; j < 16; ++j) { const unsigned c = xb_ld(&bar[XB_XCNT(j)]); sum += c; cnt += (c > 0u) ? 1u : 0u; mine = (j == x) ? c : mine; }
;         if (sum == G) break;
; __device__ __forceinline__ void xcd_barrier(const XcdBarrier& b) {
;     asm volatile("s_waitcnt vmcnt(0)" ::: "memory");
;     __syncthreads();
;     if (threadIdx.x == 0) {
;         unsigned* bar = b.bar;
;         __builtin_amdgcn_s_waitcnt(0);
;         unsigned nloc = b.st[0], nx = b.st[1];
;         if (nloc == 0u) { xcd_barrier_complete(bar, b.x, nloc, nx); b.st[0] = nloc; b.st[1] = nx; }
.Lp5t_done:
.LBB0_979:
	s_cmp_gt_i32 s71, 6
	s_cselect_b64 s[0:1], -1, 0
	s_and_b64 s[4:5], s[14:15], s[0:1]
	s_andn2_b64 vcc, exec, s[4:5]
	s_cbranch_vccnz .LBB0_1033
	s_waitcnt vmcnt(0)
	s_waitcnt lgkmcnt(0)
	s_barrier
	s_and_saveexec_b64 s[4:5], s[12:13]
	s_cbranch_execz .LBB0_1032
	s_add_i32 s6, 0, 0x26020
	v_mov_b32_e32 v0, s6
	s_waitcnt vmcnt(0) expcnt(0) lgkmcnt(0)
	ds_read_b32 v2, v0
	s_add_i32 s6, 0, 0x26024
	v_mov_b32_e32 v0, s6
	ds_read_b32 v0, v0
	s_waitcnt lgkmcnt(1)
	v_cmp_ne_u32_e32 vcc, 0, v2
	s_cbranch_vccnz .LBB0_996
	v_readlane_b32 s6, v250, 0
	v_readlane_b32 s7, v250, 1
	s_load_dwordx2 s[10:11], s[6:7], 0x4
	s_add_u32 s6, s68, 0x4200
	s_addc_u32 s7, s69, 0
	s_add_u32 s8, s68, 0x4400
	s_addc_u32 s9, s69, 0
	s_waitcnt lgkmcnt(0)
	s_mul_i32 s33, s10, s3
	s_add_u32 s10, s68, 0x4500
	s_mul_i32 s33, s33, s11
	s_addc_u32 s11, s69, 0
	s_add_u32 s14, s68, 0x4600
	s_addc_u32 s15, s69, 0
	s_add_u32 s22, s68, 0x4700
	s_addc_u32 s23, s69, 0
	s_add_u32 s38, s68, 0x4800
	s_addc_u32 s39, s69, 0
	s_add_u32 s44, s68, 0x4900
	s_addc_u32 s45, s69, 0
	s_add_u32 s46, s68, 0x4a00
	s_addc_u32 s47, s69, 0
	s_add_u32 s48, s68, 0x4b00
	s_addc_u32 s49, s69, 0
	s_add_u32 s50, s68, 0x4c00
	s_addc_u32 s51, s69, 0
	s_add_u32 s52, s68, 0x4d00
	s_addc_u32 s53, s69, 0
	s_add_u32 s54, s68, 0x4e00
	s_addc_u32 s55, s69, 0
	s_add_u32 s56, s68, 0x4f00
	s_addc_u32 s57, s69, 0
	s_add_u32 s58, s68, 0x5000
	s_addc_u32 s59, s69, 0
	s_add_u32 s60, s68, 0x5100
	s_addc_u32 s61, s69, 0
	s_add_u32 s62, s68, 0x5200
	s_addc_u32 s63, s69, 0
	s_add_u32 s64, s68, 0x5300
	s_addc_u32 s65, s69, 0
	s_mov_b32 s34, 1
	v_mov_b32_e32 v16, 0
	s_branch .LBB0_984
